# dead SGPR-spill reloads/stores in prep loop and EpiResidNorm false epilogue replaced by equivalent s_nop wait states (liveness-proven dead)
# speedup vs baseline: 1.0093x; 1.0093x over previous
; __device__ __forceinline__ float fexp(float x) { return __builtin_amdgcn_exp2f(x * 1.4426950408889634f); }
; __device__ __forceinline__ float flog(float x) { return __builtin_amdgcn_logf(x) * 0.6931471805599453f; }
; __device__ __forceinline__ void phase_dnprep(h16* Pdn, const h16* halo, const float* bd, const float* convw, const float* a_log, const float* dt_bias,
;                              h16* Tg, h16* qkg, float* gcg, float* betag, float* s2g, LAS unsigned char* ldsl, unsigned char* ldsb) {
;     ...
;         if (w == 0) {
;             const float br = pbr, ar = par_;
;             const float beta = 1.0f / (1.0f + fexp(-br));
;             const float xs = ar + dt_bias[h];
;             const float sp = (xs > 20.f) ? xs : flog(1.0f + fexp(xs));
;             float gg = -fexp(a_log[h]) * sp;
; #pragma unroll
;             for (int o = 1; o < 64; o <<= 1) { const float t = __int_as_float(__builtin_amdgcn_ds_bpermute(((lane >= o) ? (lane - o) : lane) << 2, __float_as_int(gg))); if (lane >= o) gg += t; }
;             gcs[lane] = gg; bts[lane] = beta;
;             {
;                 const float eg = fexp(gg), glast = __int_as_float(__builtin_amdgcn_readlane(__float_as_int(gg), 63));
;                 gst(gcg + bh0 + lane, eg); gst(betag + bh0 + lane, beta * eg); gst(s2g + bh0 + lane, fexp(glast - gg));
;             }
;         }
.LBB0_325:
	s_or_b64 exec, exec, s[0:1]
	s_ashr_i32 s20, s25, 9
	s_bfe_u32 s3, s25, 0x30006
	s_lshl_b32 s0, s20, 15
	s_lshl_b32 s1, s3, 12
	v_cndmask_b32_e64 v0, 0, 1, s[14:15]
	v_and_b32_e32 v99, 63, v82
	s_lshl_b32 s21, s4, 6
	s_or_b32 s0, s1, s0
	v_cmp_ne_u32_e64 s[4:5], 1, v0
	v_lshlrev_b32_e32 v0, 2, v82
	s_or_b32 s26, s0, s21
	s_andn2_b64 vcc, exec, s[14:15]
	v_lshlrev_b32_e32 v4, 2, v99
	v_cmp_gt_u32_e64 s[6:7], 16, v99
	v_and_b32_e32 v98, 0x7c, v0
	s_cbranch_vccnz .LBB0_327
	v_readlane_b32 s0, v255, 56
	s_nop 3
	s_xor_b32 s0, s0, s3
	s_bfe_u32 s0, s0, 0x10002
	s_add_i32 s1, s0, 52
	s_add_i32 s0, s0, 54
	s_nop 3
	v_readlane_b32 s1, v255, s1
	v_readlane_b32 s0, v255, s0
	s_nop 3
	v_mov_b32_e32 v2, s1
	v_mov_b32_e32 v1, s0
	s_mov_b32 s0, 0x41a00000
	v_mul_f32_e32 v0, 0xbfb8aa3b, v96
	v_exp_f32_e32 v0, v0
	s_nop 0
	v_readlane_b32 s69, v254, 52
	s_mov_b32 s27, s69
	v_add_f32_e32 v0, 1.0, v0
	s_nop 7
	s_nop 5
	v_add_f32_e32 v2, v97, v2
	v_mul_f32_e32 v3, 0x3fb8aa3b, v2
	v_exp_f32_e32 v3, v3
	v_mul_f32_e32 v1, 0x3fb8aa3b, v1
	v_exp_f32_e32 v1, v1
	v_cmp_lt_f32_e32 vcc, s0, v2
	v_add_f32_e32 v3, 1.0, v3
	v_log_f32_e32 v3, v3
	s_nop 0
	v_mul_f32_e32 v3, 0x3f317218, v3
	v_cndmask_b32_e32 v2, v3, v2, vcc
	v_cmp_ne_u32_e32 vcc, 0, v99
	v_mul_f32_e64 v3, v2, -v1
	s_nop 0
	v_subbrev_co_u32_e64 v5, s[0:1], 0, v99, vcc
	v_lshlrev_b32_e32 v5, 2, v5
	ds_bpermute_b32 v5, v5, v3
	s_waitcnt lgkmcnt(0)
	v_fma_f32 v1, v2, -v1, v5
	v_cndmask_b32_e32 v1, v3, v1, vcc
	v_cmp_gt_u32_e32 vcc, 2, v99
	s_nop 1
	v_cndmask_b32_e64 v2, -2, 0, vcc
	v_add_lshl_u32 v2, v2, v99, 2
	ds_bpermute_b32 v2, v2, v1
	s_waitcnt lgkmcnt(0)
	v_add_f32_e32 v2, v1, v2
	v_cndmask_b32_e32 v1, v2, v1, vcc
	v_cmp_gt_u32_e32 vcc, 4, v99
	s_nop 1
	v_cndmask_b32_e64 v2, -4, 0, vcc
	v_add_lshl_u32 v2, v2, v99, 2
	ds_bpermute_b32 v2, v2, v1
	s_waitcnt lgkmcnt(0)
	v_add_f32_e32 v2, v1, v2
	v_cndmask_b32_e32 v1, v2, v1, vcc
	v_cmp_gt_u32_e32 vcc, 8, v99
	s_nop 1
	v_cndmask_b32_e64 v2, -8, 0, vcc
	v_add_lshl_u32 v2, v2, v99, 2
	ds_bpermute_b32 v2, v2, v1
	s_waitcnt lgkmcnt(0)
	v_add_f32_e32 v2, v1, v2
	v_cndmask_b32_e32 v1, v2, v1, vcc
	v_cndmask_b32_e64 v2, -16, 0, s[6:7]
	v_add_lshl_u32 v2, v2, v99, 2
	ds_bpermute_b32 v2, v2, v1
	v_cmp_gt_u32_e32 vcc, 32, v99
	s_waitcnt lgkmcnt(0)
	v_add_f32_e32 v2, v1, v2
	v_cndmask_b32_e64 v1, v2, v1, s[6:7]
	ds_bpermute_b32 v2, v98, v1
	v_readlane_b32 s7, v255, 36
	s_waitcnt lgkmcnt(0)
	v_add_f32_e32 v2, v1, v2
	v_cndmask_b32_e32 v1, v2, v1, vcc
	v_div_scale_f32 v2, s[0:1], v0, v0, 1.0
	v_rcp_f32_e32 v3, v2
	s_lshl_b64 s[0:1], s[26:27], 2
	s_add_u32 s10, s80, s0
	s_addc_u32 s11, s81, s1
	v_fma_f32 v5, -v2, v3, 1.0
	v_fmac_f32_e32 v3, v5, v3
	v_div_scale_f32 v5, vcc, 1.0, v0, 1.0
	v_mul_f32_e32 v6, v5, v3
	v_fma_f32 v7, -v2, v6, v5
	v_fmac_f32_e32 v6, v7, v3
	v_fma_f32 v2, -v2, v6, v5
	v_div_fmas_f32 v2, v2, v3, v6
	v_div_fixup_f32 v0, v2, v0, 1.0
	v_add_u32_e32 v2, 0, v4
	v_add_u32_e32 v3, 0x27600, v2
	v_add_u32_e32 v2, 0x27700, v2
	ds_write_b32 v2, v0
	v_mul_f32_e32 v2, 0x3fb8aa3b, v1
	v_exp_f32_e32 v2, v2
	v_readlane_b32 s6, v1, 63
	ds_write_b32 v3, v1
	global_store_dword v4, v2, s[10:11]
	s_add_u32 s10, s7, s0
	v_readlane_b32 s7, v255, 38
	s_addc_u32 s11, s7, s1
	v_mul_f32_e32 v0, v0, v2
	global_store_dword v4, v0, s[10:11]
	v_sub_f32_e32 v0, s6, v1
	v_mul_f32_e32 v0, 0x3fb8aa3b, v0
	v_exp_f32_e32 v0, v0
	v_readlane_b32 s7, v255, 32
	s_add_u32 s0, s7, s0
	v_readlane_b32 s7, v255, 35
	s_addc_u32 s1, s7, s1
	global_store_dword v4, v0, s[0:1]

.LBB0_348:
	s_or_b64 exec, exec, s[0:1]
	s_nop 0
	v_readlane_b32 s69, v254, 52
	s_mov_b32 s45, s69
	s_lshl_b32 s44, s6, 2
	s_mov_b32 s49, s69
	s_nop 7
	s_nop 6
	v_and_b32_e32 v2, 0xfffffc00, v6
	v_ashrrev_i32_e32 v3, 31, v2
	s_nop 7
	v_writelane_b32 v254, s49, 52
	s_nop 0
	v_writelane_b32 v254, s51, 54
	v_writelane_b32 v254, s52, 55
	v_lshl_add_u64 v[2:3], v[2:3], 2, s[92:93]
	v_writelane_b32 v254, s53, 56
	v_and_b32_e32 v0, 0x7f, v1
	s_movk_i32 s0, 0x180
	s_nop 0
	v_lshl_add_u64 v[2:3], v[2:3], 0, s[44:45]
	v_lshlrev_b32_e32 v32, 2, v0
	v_cmp_gt_i32_e64 s[0:1], s0, v1
	s_nop 0
	v_lshl_add_u64 v[0:1], v[2:3], 0, v[32:33]
	s_and_saveexec_b64 s[6:7], s[0:1]
	s_cbranch_execnz .LBB0_418
	s_or_b64 exec, exec, s[6:7]
	s_and_saveexec_b64 s[6:7], s[0:1]
	s_cbranch_execnz .LBB0_419

; __device__ __forceinline__ float shx(float v, int m, int lane) { return __int_as_float(__builtin_amdgcn_ds_bpermute((lane ^ m) << 2, __float_as_int(v))); }
; __device__ __forceinline__ float silu_f(float x) { return x * __builtin_amdgcn_rcpf(1.0f + fexp(-x)); }
; __device__ __forceinline__ void phase_dnprep(h16* Pdn, const h16* halo, const float* bd, const float* convw, const float* a_log, const float* dt_bias,
;                              h16* Tg, h16* qkg, float* gcg, float* betag, float* s2g, LAS unsigned char* ldsl, unsigned char* ldsb) {
;     ...
;         {
;             const int rr = lane >> 3, cp = lane & 7, i = 8 * w + rr;
;             h16* gp = Pdn + (tok0 + i) * 4096 + h * 128 + 16 * cp;
;             const float bt_i = bts[i];
; #pragma unroll
;             for (int seg = 0; seg < 3; ++seg) {
;                 float y[16];
; #pragma unroll
;                 for (int e = 0; e < 16; ++e) y[e] = 0.f;
; #pragma unroll
;                 for (int j = 0; j < 4; ++j) {
;                     const h16x8 x0 = *(const h16x8*)(raw + (i + j) * RP + seg * 128 + 16 * cp), x1 = *(const h16x8*)(raw + (i + j) * RP + seg * 128 + 16 * cp + 8);
;                     const f32x4* cwp = (const f32x4*)(cw + j * 384 + seg * 128 + 16 * cp);
;                     const f32x4 c0 = cwp[0], c1 = cwp[1], c2 = cwp[2], c3 = cwp[3];
; #pragma unroll
;                     for (int e = 0; e < 4; ++e) {
;                         y[e] += c0[e] * (float)x0[e]; y[4 + e] += c1[e] * (float)x0[4 + e];
;                         y[8 + e] += c2[e] * (float)x1[e]; y[12 + e] += c3[e] * (float)x1[4 + e];
;                     }
;                 }
; #pragma unroll
;                 for (int e = 0; e < 16; ++e) y[e] = silu_f(y[e]);
;                 float scl = bt_i;
;                 if (seg < 2) {
;                     float ss = 0.f;
; #pragma unroll
;                     for (int e = 0; e < 16; ++e) ss += y[e] * y[e];
;                     ss += shx(ss, 1, lane); ss += shx(ss, 2, lane); ss += shx(ss, 4, lane);
;                     scl = rsqrtf(ss + 1e-6f) * (seg == 0 ? 0.08838834764831845f : 1.0f);
.LBB0_353:
	v_or_b32_e32 v0, s23, v5
	v_readlane_b32 s0, v255, 33
	s_nop 0
	v_lshlrev_b32_e32 v32, 4, v0
	v_readlane_b32 s1, v255, 34
	v_readlane_b32 s69, v254, 52
	s_mov_b32 s45, s69
	v_lshl_add_u64 v[0:1], v[32:33], 2, s[0:1]
	s_lshl_b32 s44, s22, 2
	s_mov_b32 s49, s69
	s_nop 7
	s_nop 6
	s_nop 1
	v_lshl_add_u64 v[0:1], v[0:1], 0, s[44:45]
	global_load_dword v96, v[0:1], off
	global_load_dword v97, v[0:1], off offset:32
	s_nop 7
	v_writelane_b32 v254, s49, 52
	s_nop 0
	v_writelane_b32 v254, s51, 54
	v_writelane_b32 v254, s52, 55
	v_writelane_b32 v254, s53, 56
	s_nop 1
.LBB0_354:
	s_nop 0
	s_nop 0
	v_readlane_b32 s69, v254, 52
	v_lshrrev_b32_e32 v0, 3, v99
	s_mov_b32 s45, s69
	v_or_b32_e32 v2, s37, v0
	s_nop 7
	s_nop 0
	v_readlane_b32 s71, v254, 54
	v_readlane_b32 s72, v254, 55
	v_readlane_b32 s73, v254, 56
	s_nop 1
	v_writelane_b32 v254, s36, 43
	s_lshl_b32 s0, s20, 12
	s_or_b32 s0, s0, s21
	v_writelane_b32 v254, s37, 44
	v_writelane_b32 v254, s38, 45
	v_writelane_b32 v254, s39, 46
	v_writelane_b32 v254, s40, 47
	v_writelane_b32 v254, s41, 48
	v_writelane_b32 v254, s42, 49
	v_writelane_b32 v254, s43, 50
	v_writelane_b32 v254, s44, 51
	v_writelane_b32 v254, s45, 52
	v_add_lshl_u32 v32, s0, v2, 12
	v_writelane_b32 v254, s46, 53
	v_lshlrev_b32_e32 v3, 4, v82
	v_lshl_add_u64 v[0:1], v[32:33], 1, s[86:87]
	s_mov_b32 s21, s69
	s_lshl_b32 s20, s3, 8
	v_writelane_b32 v254, s47, 54
	v_and_b32_e32 v3, 0x70, v3
	v_writelane_b32 v254, s48, 55
	v_lshl_add_u64 v[0:1], v[0:1], 0, s[20:21]
	v_lshlrev_b32_e32 v32, 1, v3
	v_writelane_b32 v254, s49, 56
	v_lshl_add_u64 v[86:87], v[0:1], 0, v[32:33]
	v_lshl_add_u32 v0, v2, 2, 0
	v_writelane_b32 v254, s50, 57
	v_add_u32_e32 v0, 0x27700, v0
	v_writelane_b32 v254, s51, 58
	ds_read_b32 v88, v0
	v_lshl_add_u32 v0, v3, 2, 0
	s_movk_i32 s0, 0x110
	v_add_u32_e32 v83, 0x25e00, v0
	v_mul_lo_u32 v0, v2, s0
	v_readlane_b32 s1, v254, 39
	v_readlane_b32 s0, v254, 38
	v_xor_b32_e32 v104, 4, v4
	v_add3_u32 v105, s1, v32, v0
	s_movk_i32 s1, 0x300
	v_add3_u32 v101, s0, v32, v0
	v_mul_lo_u32 v0, v2, s1
	v_add3_u32 v32, s78, v32, v0
	v_xor_b32_e32 v103, 8, v4
	v_xor_b32_e32 v102, 16, v4
	ds_read_b128 v[0:3], v32
	ds_read_b128 v[50:53], v32 offset:16
	ds_read_b128 v[38:41], v83
	ds_read_b128 v[8:11], v83 offset:16
	ds_read_b128 v[106:109], v83 offset:32
	ds_read_b128 v[58:61], v83 offset:48
	ds_read_b128 v[4:7], v32 offset:768
	ds_read_b128 v[54:57], v32 offset:784
	ds_read_b128 v[42:45], v83 offset:1536
	ds_read_b128 v[20:23], v83 offset:1552
	ds_read_b128 v[110:113], v83 offset:1568
	ds_read_b128 v[70:73], v83 offset:1584
	ds_read_b128 v[16:19], v32 offset:1536
	ds_read_b128 v[66:69], v32 offset:1552
	ds_read_b128 v[46:49], v83 offset:3072
	ds_read_b128 v[28:31], v83 offset:3088
	ds_read_b128 v[114:117], v83 offset:3104
	ds_read_b128 v[78:81], v83 offset:3120
	ds_read_b128 v[24:27], v32 offset:2304
	ds_read_b128 v[74:77], v32 offset:2320
	ds_read_b128 v[34:37], v83 offset:4608
	ds_read_b128 v[12:15], v83 offset:4624
	ds_read_b128 v[118:121], v83 offset:4640
	ds_read_b128 v[62:65], v83 offset:4656
	s_waitcnt lgkmcnt(0)
	v_cvt_f32_f16_e32 v90, v50
	v_cvt_f32_f16_sdwa v91, v50 dst_sel:DWORD dst_unused:UNUSED_PAD src0_sel:WORD_1
	v_cvt_f32_f16_e32 v92, v54
	v_cvt_f32_f16_sdwa v93, v54 dst_sel:DWORD dst_unused:UNUSED_PAD src0_sel:WORD_1
	v_cvt_f32_f16_e32 v54, v55
	v_pk_fma_f32 v[90:91], v[106:107], v[90:91], 0 op_sel_hi:[1,1,0]
	v_cvt_f32_f16_sdwa v55, v55 dst_sel:DWORD dst_unused:UNUSED_PAD src0_sel:WORD_1
	v_pk_fma_f32 v[90:91], v[110:111], v[92:93], v[90:91]
	v_cvt_f32_f16_e32 v92, v66
	v_cvt_f32_f16_sdwa v93, v66 dst_sel:DWORD dst_unused:UNUSED_PAD src0_sel:WORD_1
	v_cvt_f32_f16_e32 v66, v52
	s_mov_b32 s1, 0x800000
	v_and_b32_e32 v100, 15, v82
	v_pk_fma_f32 v[90:91], v[114:115], v[92:93], v[90:91]
	v_cvt_f32_f16_e32 v92, v74
	v_cvt_f32_f16_sdwa v93, v74 dst_sel:DWORD dst_unused:UNUSED_PAD src0_sel:WORD_1
	v_lshrrev_b32_e32 v84, 4, v99
	v_pk_fma_f32 v[90:91], v[118:119], v[92:93], v[90:91]
	s_nop 0
	v_mul_f32_e32 v50, 0xbfb8aa3b, v90
	v_exp_f32_e32 v50, v50
	s_nop 0
	v_add_f32_e32 v50, 1.0, v50
	v_rcp_f32_e32 v92, v50
	v_mul_f32_e32 v50, 0xbfb8aa3b, v91
	v_exp_f32_e32 v50, v50
	s_nop 0
	v_add_f32_e32 v50, 1.0, v50
	v_rcp_f32_e32 v93, v50
	v_cvt_f32_f16_e32 v50, v51
	v_cvt_f32_f16_sdwa v51, v51 dst_sel:DWORD dst_unused:UNUSED_PAD src0_sel:WORD_1
	v_pk_mul_f32 v[90:91], v[90:91], v[92:93]
	s_nop 0
	v_pk_mul_f32 v[92:93], v[90:91], v[90:91]
	v_pk_fma_f32 v[50:51], v[108:109], v[50:51], 0 op_sel_hi:[1,1,0]
	s_nop 0
	v_pk_fma_f32 v[50:51], v[112:113], v[54:55], v[50:51]
	v_cvt_f32_f16_e32 v54, v67
	v_cvt_f32_f16_sdwa v55, v67 dst_sel:DWORD dst_unused:UNUSED_PAD src0_sel:WORD_1
	v_cvt_f32_f16_sdwa v67, v52 dst_sel:DWORD dst_unused:UNUSED_PAD src0_sel:WORD_1
	v_pk_fma_f32 v[50:51], v[116:117], v[54:55], v[50:51]
	v_pk_fma_f32 v[58:59], v[58:59], v[66:67], 0 op_sel_hi:[1,1,0]
	v_cvt_f32_f16_e32 v66, v56
	v_cvt_f32_f16_sdwa v67, v56 dst_sel:DWORD dst_unused:UNUSED_PAD src0_sel:WORD_1
	v_cvt_f32_f16_e32 v56, v57
	v_cvt_f32_f16_sdwa v57, v57 dst_sel:DWORD dst_unused:UNUSED_PAD src0_sel:WORD_1
	v_cvt_f32_f16_e32 v54, v75
	v_pk_fma_f32 v[58:59], v[70:71], v[66:67], v[58:59]
	v_cvt_f32_f16_e32 v66, v68
	v_cvt_f32_f16_sdwa v67, v68 dst_sel:DWORD dst_unused:UNUSED_PAD src0_sel:WORD_1
	v_cvt_f32_f16_sdwa v55, v75 dst_sel:DWORD dst_unused:UNUSED_PAD src0_sel:WORD_1
	v_pk_fma_f32 v[58:59], v[78:79], v[66:67], v[58:59]
	v_cvt_f32_f16_e32 v66, v76
	v_cvt_f32_f16_sdwa v67, v76 dst_sel:DWORD dst_unused:UNUSED_PAD src0_sel:WORD_1
	v_pk_fma_f32 v[50:51], v[120:121], v[54:55], v[50:51]
	v_pk_fma_f32 v[58:59], v[62:63], v[66:67], v[58:59]
	s_nop 0
; __device__ __forceinline__ float shx(float v, int m, int lane) { return __int_as_float(__builtin_amdgcn_ds_bpermute((lane ^ m) << 2, __float_as_int(v))); }
; __device__ __forceinline__ float silu_f(float x) { return x * __builtin_amdgcn_rcpf(1.0f + fexp(-x)); }
; __device__ __forceinline__ void phase_dnprep(h16* Pdn, const h16* halo, const float* bd, const float* convw, const float* a_log, const float* dt_bias,
;                              h16* Tg, h16* qkg, float* gcg, float* betag, float* s2g, LAS unsigned char* ldsl, unsigned char* ldsb) {
;     ...
;                 for (int j = 0; j < 4; ++j) {
;                     const h16x8 x0 = *(const h16x8*)(raw + (i + j) * RP + seg * 128 + 16 * cp), x1 = *(const h16x8*)(raw + (i + j) * RP + seg * 128 + 16 * cp + 8);
;                     const f32x4* cwp = (const f32x4*)(cw + j * 384 + seg * 128 + 16 * cp);
;                     const f32x4 c0 = cwp[0], c1 = cwp[1], c2 = cwp[2], c3 = cwp[3];
; #pragma unroll
;                     for (int e = 0; e < 4; ++e) {
;                         y[e] += c0[e] * (float)x0[e]; y[4 + e] += c1[e] * (float)x0[4 + e];
;                         y[8 + e] += c2[e] * (float)x1[e]; y[12 + e] += c3[e] * (float)x1[4 + e];
;                     }
;                 }
; #pragma unroll
;                 for (int e = 0; e < 16; ++e) y[e] = silu_f(y[e]);
;                 float scl = bt_i;
;                 if (seg < 2) {
;                     float ss = 0.f;
; #pragma unroll
;                     for (int e = 0; e < 16; ++e) ss += y[e] * y[e];
;                     ss += shx(ss, 1, lane); ss += shx(ss, 2, lane); ss += shx(ss, 4, lane);
	v_mul_f32_e32 v52, 0xbfb8aa3b, v58
	v_exp_f32_e32 v52, v52
	v_mul_f32_e32 v54, 0xbfb8aa3b, v50
	v_mul_f32_e32 v55, 0xbfb8aa3b, v51
	v_exp_f32_e32 v54, v54
	v_add_f32_e32 v52, 1.0, v52
	v_rcp_f32_e32 v62, v52
	v_mul_f32_e32 v52, 0xbfb8aa3b, v59
	v_exp_f32_e32 v52, v52
	v_exp_f32_e32 v55, v55
	v_add_f32_e32 v54, 1.0, v54
	v_rcp_f32_e32 v54, v54
	v_add_f32_e32 v52, 1.0, v52
	v_rcp_f32_e32 v63, v52
	v_cvt_f32_f16_e32 v52, v53
	v_cvt_f32_f16_sdwa v53, v53 dst_sel:DWORD dst_unused:UNUSED_PAD src0_sel:WORD_1
	v_add_f32_e32 v55, 1.0, v55
	v_rcp_f32_e32 v55, v55
	v_pk_mul_f32 v[58:59], v[58:59], v[62:63]
	v_pk_fma_f32 v[52:53], v[60:61], v[52:53], 0 op_sel_hi:[1,1,0]
	v_cvt_f32_f16_e32 v60, v0
	v_cvt_f32_f16_sdwa v61, v0 dst_sel:DWORD dst_unused:UNUSED_PAD src0_sel:WORD_1
	v_pk_fma_f32 v[52:53], v[72:73], v[56:57], v[52:53]
	v_cvt_f32_f16_e32 v56, v69
	v_cvt_f32_f16_sdwa v57, v69 dst_sel:DWORD dst_unused:UNUSED_PAD src0_sel:WORD_1
	v_pk_fma_f32 v[38:39], v[38:39], v[60:61], 0 op_sel_hi:[1,1,0]
	v_cvt_f32_f16_e32 v60, v4
	v_cvt_f32_f16_sdwa v61, v4 dst_sel:DWORD dst_unused:UNUSED_PAD src0_sel:WORD_1
	v_cvt_f32_f16_e32 v4, v5
	v_cvt_f32_f16_sdwa v5, v5 dst_sel:DWORD dst_unused:UNUSED_PAD src0_sel:WORD_1
	v_pk_fma_f32 v[52:53], v[80:81], v[56:57], v[52:53]
	v_pk_fma_f32 v[38:39], v[42:43], v[60:61], v[38:39]
	v_cvt_f32_f16_e32 v42, v16
	v_cvt_f32_f16_sdwa v43, v16 dst_sel:DWORD dst_unused:UNUSED_PAD src0_sel:WORD_1
	v_cvt_f32_f16_e32 v16, v2
	v_cvt_f32_f16_e32 v56, v77
	v_cvt_f32_f16_sdwa v57, v77 dst_sel:DWORD dst_unused:UNUSED_PAD src0_sel:WORD_1
	v_pk_fma_f32 v[38:39], v[46:47], v[42:43], v[38:39]
	v_cvt_f32_f16_e32 v42, v24
	v_cvt_f32_f16_sdwa v43, v24 dst_sel:DWORD dst_unused:UNUSED_PAD src0_sel:WORD_1
	v_pk_fma_f32 v[52:53], v[64:65], v[56:57], v[52:53]
	v_pk_mul_f32 v[50:51], v[50:51], v[54:55]
	v_mul_f32_e32 v56, 0xbfb8aa3b, v52
	v_pk_fma_f32 v[34:35], v[34:35], v[42:43], v[38:39]
	v_mul_f32_e32 v57, 0xbfb8aa3b, v53
	v_mul_f32_e32 v0, 0xbfb8aa3b, v34
	v_exp_f32_e32 v0, v0
	v_exp_f32_e32 v56, v56
	v_exp_f32_e32 v57, v57
	v_pk_mul_f32 v[54:55], v[50:51], v[50:51]
	v_add_f32_e32 v0, 1.0, v0
	v_rcp_f32_e32 v38, v0
	v_mul_f32_e32 v0, 0xbfb8aa3b, v35
	v_exp_f32_e32 v0, v0
	v_add_f32_e32 v56, 1.0, v56
	v_add_f32_e32 v57, 1.0, v57
	v_rcp_f32_e32 v56, v56
	v_add_f32_e32 v0, 1.0, v0
	v_rcp_f32_e32 v39, v0
	v_cvt_f32_f16_e32 v0, v1
	v_cvt_f32_f16_sdwa v1, v1 dst_sel:DWORD dst_unused:UNUSED_PAD src0_sel:WORD_1
	v_rcp_f32_e32 v57, v57
	v_pk_mul_f32 v[34:35], v[34:35], v[38:39]
	v_pk_mul_f32 v[62:63], v[58:59], v[58:59]
	v_pk_fma_f32 v[0:1], v[40:41], v[0:1], 0 op_sel_hi:[1,1,0]
	v_pk_mul_f32 v[38:39], v[34:35], v[34:35]
	v_pk_fma_f32 v[0:1], v[44:45], v[4:5], v[0:1]
	v_cvt_f32_f16_e32 v4, v17
	v_cvt_f32_f16_sdwa v5, v17 dst_sel:DWORD dst_unused:UNUSED_PAD src0_sel:WORD_1
	v_cvt_f32_f16_sdwa v17, v2 dst_sel:DWORD dst_unused:UNUSED_PAD src0_sel:WORD_1
	v_pk_mul_f32 v[52:53], v[52:53], v[56:57]
	v_pk_fma_f32 v[0:1], v[48:49], v[4:5], v[0:1]
	v_pk_fma_f32 v[8:9], v[8:9], v[16:17], 0 op_sel_hi:[1,1,0]
	v_cvt_f32_f16_e32 v16, v6
	v_cvt_f32_f16_sdwa v17, v6 dst_sel:DWORD dst_unused:UNUSED_PAD src0_sel:WORD_1
	v_cvt_f32_f16_e32 v6, v7
	v_cvt_f32_f16_sdwa v7, v7 dst_sel:DWORD dst_unused:UNUSED_PAD src0_sel:WORD_1
	v_cvt_f32_f16_e32 v4, v25
	v_pk_fma_f32 v[8:9], v[20:21], v[16:17], v[8:9]
	v_cvt_f32_f16_e32 v16, v18
	v_cvt_f32_f16_sdwa v17, v18 dst_sel:DWORD dst_unused:UNUSED_PAD src0_sel:WORD_1
	v_cvt_f32_f16_sdwa v5, v25 dst_sel:DWORD dst_unused:UNUSED_PAD src0_sel:WORD_1
	v_pk_mul_f32 v[56:57], v[52:53], v[52:53]
	v_pk_fma_f32 v[8:9], v[28:29], v[16:17], v[8:9]
	v_cvt_f32_f16_e32 v16, v26
	v_cvt_f32_f16_sdwa v17, v26 dst_sel:DWORD dst_unused:UNUSED_PAD src0_sel:WORD_1
	v_pk_fma_f32 v[0:1], v[36:37], v[4:5], v[0:1]
	v_pk_fma_f32 v[8:9], v[12:13], v[16:17], v[8:9]
	s_nop 0
	v_mul_f32_e32 v2, 0xbfb8aa3b, v8
	v_exp_f32_e32 v2, v2
	v_mul_f32_e32 v4, 0xbfb8aa3b, v0
	v_mul_f32_e32 v5, 0xbfb8aa3b, v1
	v_exp_f32_e32 v4, v4
	v_add_f32_e32 v2, 1.0, v2
	v_rcp_f32_e32 v12, v2
	v_mul_f32_e32 v2, 0xbfb8aa3b, v9
	v_exp_f32_e32 v2, v2
	v_exp_f32_e32 v5, v5
	v_add_f32_e32 v4, 1.0, v4
	v_rcp_f32_e32 v4, v4
	v_add_f32_e32 v2, 1.0, v2
	v_rcp_f32_e32 v13, v2
	v_cvt_f32_f16_e32 v2, v3
	v_cvt_f32_f16_sdwa v3, v3 dst_sel:DWORD dst_unused:UNUSED_PAD src0_sel:WORD_1
	v_add_f32_e32 v5, 1.0, v5
	v_rcp_f32_e32 v5, v5
	v_pk_mul_f32 v[8:9], v[8:9], v[12:13]
	v_pk_fma_f32 v[2:3], v[10:11], v[2:3], 0 op_sel_hi:[1,1,0]
	v_pk_mul_f32 v[12:13], v[8:9], v[8:9]
	v_pk_fma_f32 v[2:3], v[22:23], v[6:7], v[2:3]
	v_cvt_f32_f16_e32 v6, v19
	v_cvt_f32_f16_sdwa v7, v19 dst_sel:DWORD dst_unused:UNUSED_PAD src0_sel:WORD_1
	v_pk_mul_f32 v[0:1], v[0:1], v[4:5]
	v_pk_fma_f32 v[2:3], v[30:31], v[6:7], v[2:3]
	v_cvt_f32_f16_e32 v6, v27
	v_cvt_f32_f16_sdwa v7, v27 dst_sel:DWORD dst_unused:UNUSED_PAD src0_sel:WORD_1
	v_pk_mul_f32 v[4:5], v[0:1], v[0:1]
	v_pk_fma_f32 v[2:3], v[14:15], v[6:7], v[2:3]
	s_nop 0
	v_mul_f32_e32 v6, 0xbfb8aa3b, v2
	v_mul_f32_e32 v7, 0xbfb8aa3b, v3
	v_exp_f32_e32 v6, v6
	v_exp_f32_e32 v7, v7
	v_add_f32_e32 v6, 1.0, v6
	v_add_f32_e32 v7, 1.0, v7
	v_rcp_f32_e32 v6, v6
	v_rcp_f32_e32 v7, v7
	s_nop 0
	v_pk_mul_f32 v[10:11], v[2:3], v[6:7]
	v_add_f32_e32 v6, v38, v39
	v_add_f32_e32 v4, v4, v6
	v_add_f32_e32 v4, v5, v4
	v_add_f32_e32 v4, v12, v4
	v_pk_mul_f32 v[2:3], v[10:11], v[10:11]
	v_add_f32_e32 v4, v13, v4
	v_add_f32_e32 v2, v2, v4
	v_add_f32_e32 v2, v3, v2
	v_add_f32_e32 v2, v92, v2
	v_add_f32_e32 v2, v93, v2
	v_add_f32_e32 v2, v54, v2
	v_add_f32_e32 v2, v55, v2
	v_add_f32_e32 v2, v62, v2
	v_add_f32_e32 v2, v63, v2
	v_add_f32_e32 v2, v56, v2
	v_add_f32_e32 v2, v57, v2
	ds_bpermute_b32 v3, v104, v2
	s_waitcnt lgkmcnt(0)
; __device__ __forceinline__ float shx(float v, int m, int lane) { return __int_as_float(__builtin_amdgcn_ds_bpermute((lane ^ m) << 2, __float_as_int(v))); }
; __device__ __forceinline__ float silu_f(float x) { return x * __builtin_amdgcn_rcpf(1.0f + fexp(-x)); }
; __device__ __forceinline__ void phase_dnprep(h16* Pdn, const h16* halo, const float* bd, const float* convw, const float* a_log, const float* dt_bias,
;                              h16* Tg, h16* qkg, float* gcg, float* betag, float* s2g, LAS unsigned char* ldsl, unsigned char* ldsb) {
;     ...
;                 for (int j = 0; j < 4; ++j) {
;                     const h16x8 x0 = *(const h16x8*)(raw + (i + j) * RP + seg * 128 + 16 * cp), x1 = *(const h16x8*)(raw + (i + j) * RP + seg * 128 + 16 * cp + 8);
;                     const f32x4* cwp = (const f32x4*)(cw + j * 384 + seg * 128 + 16 * cp);
;                     const f32x4 c0 = cwp[0], c1 = cwp[1], c2 = cwp[2], c3 = cwp[3];
; #pragma unroll
;                     for (int e = 0; e < 4; ++e) {
;                         y[e] += c0[e] * (float)x0[e]; y[4 + e] += c1[e] * (float)x0[4 + e];
;                         y[8 + e] += c2[e] * (float)x1[e]; y[12 + e] += c3[e] * (float)x1[4 + e];
;                     }
;                 }
; #pragma unroll
;                 for (int e = 0; e < 16; ++e) y[e] = silu_f(y[e]);
;                 float scl = bt_i;
;                 if (seg < 2) {
;                     float ss = 0.f;
; #pragma unroll
;                     for (int e = 0; e < 16; ++e) ss += y[e] * y[e];
;                     ss += shx(ss, 1, lane); ss += shx(ss, 2, lane); ss += shx(ss, 4, lane);
;                     scl = rsqrtf(ss + 1e-6f) * (seg == 0 ? 0.08838834764831845f : 1.0f);
;                 }
;                 h16x8 o0, o1;
; #pragma unroll
;                 for (int e = 0; e < 8; ++e) { o0[e] = (h16)(y[e] * scl); o1[e] = (h16)(y[8 + e] * scl); }
;                 if (seg == 0) { *(h16x8*)(qn + i * 136 + 16 * cp) = o0; *(h16x8*)(qn + i * 136 + 16 * cp + 8) = o1; }
;                 if (seg == 1) { *(h16x8*)(kn + i * 136 + 16 * cp) = o0; *(h16x8*)(kn + i * 136 + 16 * cp + 8) = o1; }
;                 gst((h16x8*)(gp + seg * 1024), o0); gst((h16x8*)(gp + seg * 1024 + 8), o1);
	v_add_f32_e32 v2, v2, v3
	ds_bpermute_b32 v3, v103, v2
	s_waitcnt lgkmcnt(0)
	v_add_f32_e32 v2, v2, v3
	ds_bpermute_b32 v3, v102, v2
	s_waitcnt lgkmcnt(0)
	v_add_f32_e32 v2, v2, v3
	v_add_f32_e32 v2, 0x358637bd, v2
	v_cmp_gt_f32_e32 vcc, s1, v2
	v_mul_f32_e32 v3, 0x4b800000, v2
	s_nop 0
	v_cndmask_b32_e32 v2, v2, v3, vcc
	v_rsq_f32_e32 v2, v2
	s_nop 0
	v_mul_f32_e32 v3, 0x45800000, v2
	v_cndmask_b32_e32 v2, v2, v3, vcc
	v_mul_f32_e32 v12, 0x3db504f3, v2
	v_pk_mul_f32 v[2:3], v[34:35], v[12:13] op_sel_hi:[1,0]
	v_pk_mul_f32 v[0:1], v[0:1], v[12:13] op_sel_hi:[1,0]
	v_cvt_pk_f16_f32 v2, v2, v3
	v_cvt_pk_f16_f32 v3, v0, v1
	v_pk_mul_f32 v[0:1], v[50:51], v[12:13] op_sel_hi:[1,0]
	v_pk_mul_f32 v[4:5], v[90:91], v[12:13] op_sel_hi:[1,0]
	v_cvt_pk_f16_f32 v7, v0, v1
	v_pk_mul_f32 v[0:1], v[8:9], v[12:13] op_sel_hi:[1,0]
	v_cvt_pk_f16_f32 v6, v4, v5
	v_cvt_pk_f16_f32 v4, v0, v1
	v_pk_mul_f32 v[0:1], v[58:59], v[12:13] op_sel_hi:[1,0]
	s_nop 0
	v_cvt_pk_f16_f32 v8, v0, v1
	v_pk_mul_f32 v[0:1], v[10:11], v[12:13] op_sel_hi:[1,0]
	s_nop 0
	v_cvt_pk_f16_f32 v5, v0, v1
	v_pk_mul_f32 v[0:1], v[52:53], v[12:13] op_sel_hi:[1,0]
	s_nop 0
	v_cvt_pk_f16_f32 v9, v0, v1
	ds_write_b128 v105, v[2:5]
	ds_write_b128 v105, v[6:9] offset:16
	global_store_dwordx4 v[86:87], v[2:5], off
	global_store_dwordx4 v[86:87], v[6:9], off offset:16
	ds_read_b128 v[24:27], v32 offset:256
	ds_read_b128 v[74:77], v32 offset:272
	ds_read_b128 v[46:49], v83 offset:512
	ds_read_b128 v[28:31], v83 offset:528
	ds_read_b128 v[106:109], v83 offset:544
	ds_read_b128 v[78:81], v83 offset:560
	ds_read_b128 v[16:19], v32 offset:1024
	ds_read_b128 v[62:65], v32 offset:1040
	ds_read_b128 v[42:45], v83 offset:2048
	ds_read_b128 v[20:23], v83 offset:2064
	ds_read_b128 v[110:113], v83 offset:2080
	ds_read_b128 v[66:69], v83 offset:2096
	ds_read_b128 v[4:7], v32 offset:1792
	ds_read_b128 v[54:57], v32 offset:1808
	ds_read_b128 v[38:41], v83 offset:3584
	ds_read_b128 v[12:15], v83 offset:3600
	ds_read_b128 v[114:117], v83 offset:3616
	ds_read_b128 v[70:73], v83 offset:3632
	ds_read_b128 v[8:11], v32 offset:2560
	ds_read_b128 v[58:61], v32 offset:2576
	ds_read_b128 v[34:37], v83 offset:5120
	ds_read_b128 v[0:3], v83 offset:5136
	ds_read_b128 v[118:121], v83 offset:5152
	ds_read_b128 v[50:53], v83 offset:5168
	s_waitcnt lgkmcnt(0)
	v_cvt_f32_f16_e32 v90, v74
	v_cvt_f32_f16_sdwa v91, v74 dst_sel:DWORD dst_unused:UNUSED_PAD src0_sel:WORD_1
	v_cvt_f32_f16_e32 v92, v62
	v_cvt_f32_f16_sdwa v93, v62 dst_sel:DWORD dst_unused:UNUSED_PAD src0_sel:WORD_1
	v_cvt_f32_f16_e32 v74, v75
	v_pk_fma_f32 v[90:91], v[106:107], v[90:91], 0 op_sel_hi:[1,1,0]
	v_cvt_f32_f16_sdwa v75, v75 dst_sel:DWORD dst_unused:UNUSED_PAD src0_sel:WORD_1
	v_pk_fma_f32 v[90:91], v[110:111], v[92:93], v[90:91]
	v_cvt_f32_f16_e32 v92, v54
	v_cvt_f32_f16_sdwa v93, v54 dst_sel:DWORD dst_unused:UNUSED_PAD src0_sel:WORD_1
	v_cvt_f32_f16_e32 v62, v63
	v_cvt_f32_f16_sdwa v63, v63 dst_sel:DWORD dst_unused:UNUSED_PAD src0_sel:WORD_1
	v_pk_fma_f32 v[74:75], v[108:109], v[74:75], 0 op_sel_hi:[1,1,0]
	v_pk_fma_f32 v[90:91], v[114:115], v[92:93], v[90:91]
	v_cvt_f32_f16_e32 v92, v58
	v_cvt_f32_f16_sdwa v93, v58 dst_sel:DWORD dst_unused:UNUSED_PAD src0_sel:WORD_1
	v_pk_fma_f32 v[62:63], v[112:113], v[62:63], v[74:75]
	v_cvt_f32_f16_e32 v74, v64
	v_cvt_f32_f16_sdwa v75, v64 dst_sel:DWORD dst_unused:UNUSED_PAD src0_sel:WORD_1
	v_pk_fma_f32 v[90:91], v[118:119], v[92:93], v[90:91]
	v_cvt_f32_f16_e32 v64, v65
	v_mul_f32_e32 v54, 0xbfb8aa3b, v90
	v_exp_f32_e32 v54, v54
	v_cvt_f32_f16_sdwa v65, v65 dst_sel:DWORD dst_unused:UNUSED_PAD src0_sel:WORD_1
	v_cvt_f32_f16_e32 v58, v59
	v_cvt_f32_f16_sdwa v59, v59 dst_sel:DWORD dst_unused:UNUSED_PAD src0_sel:WORD_1
	v_add_f32_e32 v54, 1.0, v54
	v_rcp_f32_e32 v92, v54
	v_mul_f32_e32 v54, 0xbfb8aa3b, v91
	v_exp_f32_e32 v54, v54
	s_nop 0
	v_add_f32_e32 v54, 1.0, v54
	v_rcp_f32_e32 v93, v54
	v_cvt_f32_f16_e32 v54, v55
	v_cvt_f32_f16_sdwa v55, v55 dst_sel:DWORD dst_unused:UNUSED_PAD src0_sel:WORD_1
	v_pk_mul_f32 v[90:91], v[90:91], v[92:93]
	s_nop 0
	v_pk_mul_f32 v[92:93], v[90:91], v[90:91]
	v_pk_fma_f32 v[54:55], v[116:117], v[54:55], v[62:63]
	v_cvt_f32_f16_e32 v62, v76
	v_cvt_f32_f16_sdwa v63, v76 dst_sel:DWORD dst_unused:UNUSED_PAD src0_sel:WORD_1
	v_pk_fma_f32 v[54:55], v[120:121], v[58:59], v[54:55]
	v_pk_fma_f32 v[62:63], v[78:79], v[62:63], 0 op_sel_hi:[1,1,0]
	s_nop 0
	v_pk_fma_f32 v[62:63], v[66:67], v[74:75], v[62:63]
	v_cvt_f32_f16_e32 v66, v56
	v_cvt_f32_f16_sdwa v67, v56 dst_sel:DWORD dst_unused:UNUSED_PAD src0_sel:WORD_1
	v_mul_f32_e32 v58, 0xbfb8aa3b, v54
	v_mul_f32_e32 v59, 0xbfb8aa3b, v55
	v_exp_f32_e32 v58, v58
	v_pk_fma_f32 v[62:63], v[70:71], v[66:67], v[62:63]
	v_cvt_f32_f16_e32 v66, v60
	v_cvt_f32_f16_sdwa v67, v60 dst_sel:DWORD dst_unused:UNUSED_PAD src0_sel:WORD_1
	v_cvt_f32_f16_e32 v60, v61
	v_cvt_f32_f16_sdwa v61, v61 dst_sel:DWORD dst_unused:UNUSED_PAD src0_sel:WORD_1
	v_exp_f32_e32 v59, v59
	v_pk_fma_f32 v[50:51], v[50:51], v[66:67], v[62:63]
	v_cvt_f32_f16_e32 v66, v77
	v_mul_f32_e32 v56, 0xbfb8aa3b, v50
	v_exp_f32_e32 v56, v56
	v_cvt_f32_f16_sdwa v67, v77 dst_sel:DWORD dst_unused:UNUSED_PAD src0_sel:WORD_1
	v_add_f32_e32 v58, 1.0, v58
	v_add_f32_e32 v59, 1.0, v59
	v_add_f32_e32 v56, 1.0, v56
	v_rcp_f32_e32 v62, v56
	v_mul_f32_e32 v56, 0xbfb8aa3b, v51
	v_exp_f32_e32 v56, v56
	v_pk_fma_f32 v[66:67], v[80:81], v[66:67], 0 op_sel_hi:[1,1,0]
	v_rcp_f32_e32 v58, v58
	v_pk_fma_f32 v[64:65], v[68:69], v[64:65], v[66:67]
	v_add_f32_e32 v56, 1.0, v56
	v_rcp_f32_e32 v63, v56
	v_cvt_f32_f16_e32 v56, v57
	v_cvt_f32_f16_sdwa v57, v57 dst_sel:DWORD dst_unused:UNUSED_PAD src0_sel:WORD_1
	v_rcp_f32_e32 v59, v59
; __device__ __forceinline__ float shx(float v, int m, int lane) { return __int_as_float(__builtin_amdgcn_ds_bpermute((lane ^ m) << 2, __float_as_int(v))); }
; __device__ __forceinline__ float silu_f(float x) { return x * __builtin_amdgcn_rcpf(1.0f + fexp(-x)); }
; __device__ __forceinline__ void phase_dnprep(h16* Pdn, const h16* halo, const float* bd, const float* convw, const float* a_log, const float* dt_bias,
;                              h16* Tg, h16* qkg, float* gcg, float* betag, float* s2g, LAS unsigned char* ldsl, unsigned char* ldsb) {
;     ...
;                 for (int j = 0; j < 4; ++j) {
;                     const h16x8 x0 = *(const h16x8*)(raw + (i + j) * RP + seg * 128 + 16 * cp), x1 = *(const h16x8*)(raw + (i + j) * RP + seg * 128 + 16 * cp + 8);
;                     const f32x4* cwp = (const f32x4*)(cw + j * 384 + seg * 128 + 16 * cp);
;                     const f32x4 c0 = cwp[0], c1 = cwp[1], c2 = cwp[2], c3 = cwp[3];
; #pragma unroll
;                     for (int e = 0; e < 4; ++e) {
;                         y[e] += c0[e] * (float)x0[e]; y[4 + e] += c1[e] * (float)x0[4 + e];
;                         y[8 + e] += c2[e] * (float)x1[e]; y[12 + e] += c3[e] * (float)x1[4 + e];
;                     }
;                 }
; #pragma unroll
;                 for (int e = 0; e < 16; ++e) y[e] = silu_f(y[e]);
;                 float scl = bt_i;
;                 if (seg < 2) {
;                     float ss = 0.f;
; #pragma unroll
;                     for (int e = 0; e < 16; ++e) ss += y[e] * y[e];
;                     ss += shx(ss, 1, lane); ss += shx(ss, 2, lane); ss += shx(ss, 4, lane);
	v_pk_mul_f32 v[50:51], v[50:51], v[62:63]
	v_pk_fma_f32 v[56:57], v[72:73], v[56:57], v[64:65]
	s_nop 0
	v_pk_fma_f32 v[52:53], v[52:53], v[60:61], v[56:57]
	v_cvt_f32_f16_e32 v60, v24
	v_cvt_f32_f16_sdwa v61, v24 dst_sel:DWORD dst_unused:UNUSED_PAD src0_sel:WORD_1
	v_cvt_f32_f16_e32 v24, v25
	v_cvt_f32_f16_sdwa v25, v25 dst_sel:DWORD dst_unused:UNUSED_PAD src0_sel:WORD_1
	v_mul_f32_e32 v56, 0xbfb8aa3b, v52
	v_pk_fma_f32 v[46:47], v[46:47], v[60:61], 0 op_sel_hi:[1,1,0]
	v_cvt_f32_f16_e32 v60, v16
	v_cvt_f32_f16_sdwa v61, v16 dst_sel:DWORD dst_unused:UNUSED_PAD src0_sel:WORD_1
	v_cvt_f32_f16_e32 v16, v17
	v_cvt_f32_f16_sdwa v17, v17 dst_sel:DWORD dst_unused:UNUSED_PAD src0_sel:WORD_1
	v_pk_fma_f32 v[24:25], v[48:49], v[24:25], 0 op_sel_hi:[1,1,0]
	v_pk_fma_f32 v[42:43], v[42:43], v[60:61], v[46:47]
	v_cvt_f32_f16_e32 v46, v4
	v_cvt_f32_f16_sdwa v47, v4 dst_sel:DWORD dst_unused:UNUSED_PAD src0_sel:WORD_1
	v_pk_fma_f32 v[16:17], v[44:45], v[16:17], v[24:25]
	v_cvt_f32_f16_e32 v24, v18
	v_cvt_f32_f16_sdwa v25, v18 dst_sel:DWORD dst_unused:UNUSED_PAD src0_sel:WORD_1
	v_pk_fma_f32 v[38:39], v[38:39], v[46:47], v[42:43]
	v_cvt_f32_f16_e32 v42, v8
	v_cvt_f32_f16_sdwa v43, v8 dst_sel:DWORD dst_unused:UNUSED_PAD src0_sel:WORD_1
	v_cvt_f32_f16_e32 v18, v19
	v_cvt_f32_f16_sdwa v19, v19 dst_sel:DWORD dst_unused:UNUSED_PAD src0_sel:WORD_1
	v_cvt_f32_f16_e32 v8, v9
	v_pk_fma_f32 v[34:35], v[34:35], v[42:43], v[38:39]
	v_cvt_f32_f16_sdwa v9, v9 dst_sel:DWORD dst_unused:UNUSED_PAD src0_sel:WORD_1
	v_mul_f32_e32 v4, 0xbfb8aa3b, v34
	v_exp_f32_e32 v4, v4
	v_mul_f32_e32 v57, 0xbfb8aa3b, v53
	v_exp_f32_e32 v56, v56
	v_exp_f32_e32 v57, v57
	v_add_f32_e32 v4, 1.0, v4
	v_rcp_f32_e32 v38, v4
	v_mul_f32_e32 v4, 0xbfb8aa3b, v35
	v_exp_f32_e32 v4, v4
	v_add_f32_e32 v56, 1.0, v56
	v_add_f32_e32 v57, 1.0, v57
	v_pk_mul_f32 v[54:55], v[54:55], v[58:59]
	v_add_f32_e32 v4, 1.0, v4
	v_rcp_f32_e32 v39, v4
	v_cvt_f32_f16_e32 v4, v5
	v_cvt_f32_f16_sdwa v5, v5 dst_sel:DWORD dst_unused:UNUSED_PAD src0_sel:WORD_1
	v_rcp_f32_e32 v56, v56
	v_pk_mul_f32 v[34:35], v[34:35], v[38:39]
	v_rcp_f32_e32 v57, v57
	v_pk_fma_f32 v[4:5], v[40:41], v[4:5], v[16:17]
	v_cvt_f32_f16_e32 v16, v26
	v_cvt_f32_f16_sdwa v17, v26 dst_sel:DWORD dst_unused:UNUSED_PAD src0_sel:WORD_1
	v_pk_fma_f32 v[4:5], v[36:37], v[8:9], v[4:5]
	v_pk_mul_f32 v[38:39], v[34:35], v[34:35]
	v_mul_f32_e32 v8, 0xbfb8aa3b, v4
	v_pk_fma_f32 v[16:17], v[28:29], v[16:17], 0 op_sel_hi:[1,1,0]
	v_mul_f32_e32 v9, 0xbfb8aa3b, v5
	v_pk_fma_f32 v[16:17], v[20:21], v[24:25], v[16:17]
	v_cvt_f32_f16_e32 v20, v6
	v_cvt_f32_f16_sdwa v21, v6 dst_sel:DWORD dst_unused:UNUSED_PAD src0_sel:WORD_1
	v_exp_f32_e32 v8, v8
	v_exp_f32_e32 v9, v9
	v_pk_mul_f32 v[58:59], v[54:55], v[54:55]
	v_pk_fma_f32 v[12:13], v[12:13], v[20:21], v[16:17]
	v_cvt_f32_f16_e32 v16, v10
	v_cvt_f32_f16_sdwa v17, v10 dst_sel:DWORD dst_unused:UNUSED_PAD src0_sel:WORD_1
	v_cvt_f32_f16_e32 v10, v11
	v_cvt_f32_f16_sdwa v11, v11 dst_sel:DWORD dst_unused:UNUSED_PAD src0_sel:WORD_1
	v_add_f32_e32 v8, 1.0, v8
	v_pk_fma_f32 v[0:1], v[0:1], v[16:17], v[12:13]
	v_cvt_f32_f16_e32 v16, v27
	v_mul_f32_e32 v6, 0xbfb8aa3b, v0
	v_exp_f32_e32 v6, v6
	v_cvt_f32_f16_sdwa v17, v27 dst_sel:DWORD dst_unused:UNUSED_PAD src0_sel:WORD_1
	v_add_f32_e32 v9, 1.0, v9
	v_rcp_f32_e32 v8, v8
	v_add_f32_e32 v6, 1.0, v6
	v_rcp_f32_e32 v12, v6
	v_mul_f32_e32 v6, 0xbfb8aa3b, v1
	v_exp_f32_e32 v6, v6
	v_pk_fma_f32 v[16:17], v[30:31], v[16:17], 0 op_sel_hi:[1,1,0]
	v_rcp_f32_e32 v9, v9
	v_pk_fma_f32 v[16:17], v[22:23], v[18:19], v[16:17]
	v_add_f32_e32 v6, 1.0, v6
	v_rcp_f32_e32 v13, v6
	v_cvt_f32_f16_e32 v6, v7
	v_cvt_f32_f16_sdwa v7, v7 dst_sel:DWORD dst_unused:UNUSED_PAD src0_sel:WORD_1
	v_pk_mul_f32 v[4:5], v[4:5], v[8:9]
	v_pk_mul_f32 v[12:13], v[0:1], v[12:13]
	v_pk_mul_f32 v[8:9], v[4:5], v[4:5]
	v_pk_fma_f32 v[6:7], v[14:15], v[6:7], v[16:17]
	v_pk_mul_f32 v[0:1], v[12:13], v[12:13]
	v_pk_fma_f32 v[2:3], v[2:3], v[10:11], v[6:7]
	v_pk_mul_f32 v[62:63], v[50:51], v[50:51]
	v_mul_f32_e32 v6, 0xbfb8aa3b, v2
	v_mul_f32_e32 v7, 0xbfb8aa3b, v3
	v_exp_f32_e32 v6, v6
	v_exp_f32_e32 v7, v7
	v_pk_mul_f32 v[52:53], v[52:53], v[56:57]
	v_add_f32_e32 v6, 1.0, v6
	v_add_f32_e32 v7, 1.0, v7
	v_rcp_f32_e32 v6, v6
	v_rcp_f32_e32 v7, v7
	v_pk_mul_f32 v[56:57], v[52:53], v[52:53]
	v_pk_mul_f32 v[10:11], v[2:3], v[6:7]
	v_add_f32_e32 v6, v38, v39
	v_add_f32_e32 v6, v8, v6
	v_add_f32_e32 v6, v9, v6
	v_add_f32_e32 v0, v0, v6
	v_pk_mul_f32 v[2:3], v[10:11], v[10:11]
	v_add_f32_e32 v0, v1, v0
	v_add_f32_e32 v0, v2, v0
	v_add_f32_e32 v0, v3, v0
	v_add_f32_e32 v0, v92, v0
	v_add_f32_e32 v0, v93, v0
	v_add_f32_e32 v0, v58, v0
	v_add_f32_e32 v0, v59, v0
	v_add_f32_e32 v0, v62, v0
	v_add_f32_e32 v0, v63, v0
	v_add_f32_e32 v0, v56, v0
	v_add_f32_e32 v0, v57, v0
	ds_bpermute_b32 v1, v104, v0
	s_waitcnt lgkmcnt(0)
	v_add_f32_e32 v0, v0, v1
	ds_bpermute_b32 v1, v103, v0
	s_waitcnt lgkmcnt(0)
	v_add_f32_e32 v0, v0, v1
	ds_bpermute_b32 v1, v102, v0
	s_waitcnt lgkmcnt(0)
; __device__ __forceinline__ float shx(float v, int m, int lane) { return __int_as_float(__builtin_amdgcn_ds_bpermute((lane ^ m) << 2, __float_as_int(v))); }
; __device__ __forceinline__ float silu_f(float x) { return x * __builtin_amdgcn_rcpf(1.0f + fexp(-x)); }
; __device__ __forceinline__ void phase_dnprep(h16* Pdn, const h16* halo, const float* bd, const float* convw, const float* a_log, const float* dt_bias,
;                              h16* Tg, h16* qkg, float* gcg, float* betag, float* s2g, LAS unsigned char* ldsl, unsigned char* ldsb) {
;     ...
;                 for (int j = 0; j < 4; ++j) {
;                     const h16x8 x0 = *(const h16x8*)(raw + (i + j) * RP + seg * 128 + 16 * cp), x1 = *(const h16x8*)(raw + (i + j) * RP + seg * 128 + 16 * cp + 8);
;                     const f32x4* cwp = (const f32x4*)(cw + j * 384 + seg * 128 + 16 * cp);
;                     const f32x4 c0 = cwp[0], c1 = cwp[1], c2 = cwp[2], c3 = cwp[3];
; #pragma unroll
;                     for (int e = 0; e < 4; ++e) {
;                         y[e] += c0[e] * (float)x0[e]; y[4 + e] += c1[e] * (float)x0[4 + e];
;                         y[8 + e] += c2[e] * (float)x1[e]; y[12 + e] += c3[e] * (float)x1[4 + e];
;                     }
;                 }
; #pragma unroll
;                 for (int e = 0; e < 16; ++e) y[e] = silu_f(y[e]);
;                 float scl = bt_i;
;                 if (seg < 2) {
;                     float ss = 0.f;
; #pragma unroll
;                     for (int e = 0; e < 16; ++e) ss += y[e] * y[e];
;                     ss += shx(ss, 1, lane); ss += shx(ss, 2, lane); ss += shx(ss, 4, lane);
;                     scl = rsqrtf(ss + 1e-6f) * (seg == 0 ? 0.08838834764831845f : 1.0f);
;                 }
;                 h16x8 o0, o1;
; #pragma unroll
;                 for (int e = 0; e < 8; ++e) { o0[e] = (h16)(y[e] * scl); o1[e] = (h16)(y[8 + e] * scl); }
;                 if (seg == 0) { *(h16x8*)(qn + i * 136 + 16 * cp) = o0; *(h16x8*)(qn + i * 136 + 16 * cp + 8) = o1; }
;                 if (seg == 1) { *(h16x8*)(kn + i * 136 + 16 * cp) = o0; *(h16x8*)(kn + i * 136 + 16 * cp + 8) = o1; }
;                 gst((h16x8*)(gp + seg * 1024), o0); gst((h16x8*)(gp + seg * 1024 + 8), o1);
;             }
	v_add_f32_e32 v0, v0, v1
	v_add_f32_e32 v0, 0x358637bd, v0
	v_cmp_gt_f32_e32 vcc, s1, v0
	v_mul_f32_e32 v1, 0x4b800000, v0
	s_movk_i32 s1, 0x1000
	v_cndmask_b32_e32 v0, v0, v1, vcc
	v_rsq_f32_e32 v0, v0
	s_nop 0
	v_mul_f32_e32 v1, 0x45800000, v0
	v_cndmask_b32_e32 v14, v0, v1, vcc
	v_pk_mul_f32 v[2:3], v[90:91], v[14:15] op_sel_hi:[1,0]
	v_pk_mul_f32 v[0:1], v[34:35], v[14:15] op_sel_hi:[1,0]
	v_cvt_pk_f16_f32 v6, v2, v3
	v_pk_mul_f32 v[2:3], v[4:5], v[14:15] op_sel_hi:[1,0]
	v_cvt_pk_f16_f32 v0, v0, v1
	v_cvt_pk_f16_f32 v1, v2, v3
	v_pk_mul_f32 v[2:3], v[54:55], v[14:15] op_sel_hi:[1,0]
	v_pk_mul_f32 v[4:5], v[50:51], v[14:15] op_sel_hi:[1,0]
	v_cvt_pk_f16_f32 v7, v2, v3
	v_pk_mul_f32 v[2:3], v[12:13], v[14:15] op_sel_hi:[1,0]
	v_cvt_pk_f16_f32 v8, v4, v5
	v_pk_mul_f32 v[4:5], v[10:11], v[14:15] op_sel_hi:[1,0]
	v_cvt_pk_f16_f32 v2, v2, v3
	v_cvt_pk_f16_f32 v3, v4, v5
	v_pk_mul_f32 v[4:5], v[52:53], v[14:15] op_sel_hi:[1,0]
	s_nop 0
	v_cvt_pk_f16_f32 v9, v4, v5
	ds_write_b128 v101, v[0:3]
	ds_write_b128 v101, v[6:9] offset:16
	global_store_dwordx4 v[86:87], v[0:3], off offset:2048
	global_store_dwordx4 v[86:87], v[6:9], off offset:2064
	ds_read_b128 v[0:3], v83 offset:5664
	ds_read_b128 v[12:15], v32 offset:2832
	ds_read_b128 v[16:19], v83 offset:4128
	ds_read_b128 v[24:27], v32 offset:2064
	ds_read_b128 v[28:31], v83 offset:2592
	ds_read_b128 v[34:37], v32 offset:1296
	ds_read_b128 v[20:23], v83 offset:1024
	ds_read_b128 v[4:7], v83 offset:1040
	ds_read_b128 v[38:41], v83 offset:1056
	ds_read_b128 v[42:45], v83 offset:1072
	ds_read_b128 v[8:11], v32 offset:512
	ds_read_b128 v[46:49], v32 offset:528
	s_waitcnt lgkmcnt(0)
	v_cvt_f32_f16_e32 v54, v34
	v_cvt_f32_f16_sdwa v55, v34 dst_sel:DWORD dst_unused:UNUSED_PAD src0_sel:WORD_1
	v_cvt_f32_f16_e32 v52, v24
	v_cvt_f32_f16_sdwa v53, v24 dst_sel:DWORD dst_unused:UNUSED_PAD src0_sel:WORD_1
	v_cvt_f32_f16_e32 v56, v46
	v_cvt_f32_f16_sdwa v57, v46 dst_sel:DWORD dst_unused:UNUSED_PAD src0_sel:WORD_1
	v_cvt_f32_f16_e32 v50, v12
	v_cvt_f32_f16_sdwa v51, v12 dst_sel:DWORD dst_unused:UNUSED_PAD src0_sel:WORD_1
	v_cvt_f32_f16_e32 v24, v35
	v_pk_fma_f32 v[38:39], v[38:39], v[56:57], 0 op_sel_hi:[1,1,0]
	v_cvt_f32_f16_e32 v34, v48
	v_pk_fma_f32 v[28:29], v[28:29], v[54:55], v[38:39]
	s_nop 0
	v_pk_fma_f32 v[16:17], v[16:17], v[52:53], v[28:29]
	v_cvt_f32_f16_e32 v28, v47
	v_pk_fma_f32 v[0:1], v[0:1], v[50:51], v[16:17]
	v_cvt_f32_f16_sdwa v29, v47 dst_sel:DWORD dst_unused:UNUSED_PAD src0_sel:WORD_1
	v_mul_f32_e32 v12, 0xbfb8aa3b, v0
	v_exp_f32_e32 v12, v12
	v_pk_fma_f32 v[28:29], v[40:41], v[28:29], 0 op_sel_hi:[1,1,0]
	v_add_f32_e32 v12, 1.0, v12
	v_rcp_f32_e32 v16, v12
	v_mul_f32_e32 v12, 0xbfb8aa3b, v1
	v_exp_f32_e32 v12, v12
	s_nop 0
	v_add_f32_e32 v12, 1.0, v12
	v_rcp_f32_e32 v17, v12
	v_cvt_f32_f16_e32 v12, v13
	v_cvt_f32_f16_sdwa v13, v13 dst_sel:DWORD dst_unused:UNUSED_PAD src0_sel:WORD_1
	v_pk_mul_f32 v[0:1], v[0:1], v[16:17]
	v_cvt_f32_f16_e32 v16, v25
	v_cvt_f32_f16_sdwa v17, v25 dst_sel:DWORD dst_unused:UNUSED_PAD src0_sel:WORD_1
	v_cvt_f32_f16_sdwa v25, v35 dst_sel:DWORD dst_unused:UNUSED_PAD src0_sel:WORD_1
	s_nop 0
	v_pk_mul_f32 v[0:1], v[88:89], v[0:1] op_sel_hi:[0,1]
	v_cvt_pk_f16_f32 v0, v0, v1
	v_cvt_f32_f16_sdwa v35, v48 dst_sel:DWORD dst_unused:UNUSED_PAD src0_sel:WORD_1
	v_pk_fma_f32 v[24:25], v[30:31], v[24:25], v[28:29]
	v_pk_fma_f32 v[34:35], v[42:43], v[34:35], 0 op_sel_hi:[1,1,0]
	v_pk_fma_f32 v[16:17], v[18:19], v[16:17], v[24:25]
	v_cvt_f32_f16_e32 v24, v36
	v_pk_fma_f32 v[2:3], v[2:3], v[12:13], v[16:17]
	ds_read_b128 v[16:19], v83 offset:5680
	ds_read_b128 v[28:31], v83 offset:4144
	ds_read_b128 v[38:41], v83 offset:2608
	v_mul_f32_e32 v1, 0xbfb8aa3b, v2
	v_exp_f32_e32 v1, v1
	v_cvt_f32_f16_sdwa v25, v36 dst_sel:DWORD dst_unused:UNUSED_PAD src0_sel:WORD_1
	v_cvt_f32_f16_e32 v42, v8
	v_cvt_f32_f16_sdwa v43, v8 dst_sel:DWORD dst_unused:UNUSED_PAD src0_sel:WORD_1
	v_add_f32_e32 v1, 1.0, v1
	v_rcp_f32_e32 v12, v1
	v_mul_f32_e32 v1, 0xbfb8aa3b, v3
	v_exp_f32_e32 v1, v1
	s_waitcnt lgkmcnt(0)
	v_pk_fma_f32 v[24:25], v[38:39], v[24:25], v[34:35]
	v_pk_fma_f32 v[20:21], v[20:21], v[42:43], 0 op_sel_hi:[1,1,0]
	v_add_f32_e32 v1, 1.0, v1
	v_rcp_f32_e32 v13, v1
	s_nop 0
	v_pk_mul_f32 v[2:3], v[2:3], v[12:13]
	s_nop 0
	v_pk_mul_f32 v[2:3], v[88:89], v[2:3] op_sel_hi:[0,1]
	v_cvt_f32_f16_e32 v12, v26
	v_cvt_f32_f16_sdwa v13, v26 dst_sel:DWORD dst_unused:UNUSED_PAD src0_sel:WORD_1
	v_cvt_pk_f16_f32 v1, v2, v3
	v_cvt_f32_f16_e32 v2, v14
	v_cvt_f32_f16_sdwa v3, v14 dst_sel:DWORD dst_unused:UNUSED_PAD src0_sel:WORD_1
	v_pk_fma_f32 v[12:13], v[28:29], v[12:13], v[24:25]
	v_cvt_f32_f16_e32 v24, v49
	v_cvt_f32_f16_sdwa v25, v49 dst_sel:DWORD dst_unused:UNUSED_PAD src0_sel:WORD_1
	v_pk_fma_f32 v[2:3], v[16:17], v[2:3], v[12:13]
	v_cvt_f32_f16_e32 v16, v37
	v_mul_f32_e32 v12, 0xbfb8aa3b, v2
	v_mul_f32_e32 v13, 0xbfb8aa3b, v3
	v_exp_f32_e32 v12, v12
	v_exp_f32_e32 v13, v13
	v_cvt_f32_f16_sdwa v17, v37 dst_sel:DWORD dst_unused:UNUSED_PAD src0_sel:WORD_1
	v_cvt_f32_f16_e32 v14, v27
	v_add_f32_e32 v12, 1.0, v12
	v_add_f32_e32 v13, 1.0, v13
	v_rcp_f32_e32 v12, v12
	v_rcp_f32_e32 v13, v13
	v_pk_fma_f32 v[24:25], v[44:45], v[24:25], 0 op_sel_hi:[1,1,0]
	v_pk_mul_f32 v[2:3], v[2:3], v[12:13]
	v_cvt_f32_f16_e32 v12, v15
	v_cvt_f32_f16_sdwa v13, v15 dst_sel:DWORD dst_unused:UNUSED_PAD src0_sel:WORD_1
	v_cvt_f32_f16_sdwa v15, v27 dst_sel:DWORD dst_unused:UNUSED_PAD src0_sel:WORD_1
	v_pk_fma_f32 v[16:17], v[40:41], v[16:17], v[24:25]
	v_pk_mul_f32 v[2:3], v[88:89], v[2:3] op_sel_hi:[0,1]
	v_cvt_pk_f16_f32 v2, v2, v3
	v_pk_fma_f32 v[14:15], v[30:31], v[14:15], v[16:17]
	s_nop 0
	v_pk_fma_f32 v[12:13], v[18:19], v[12:13], v[14:15]
	s_nop 0
	v_mul_f32_e32 v3, 0xbfb8aa3b, v12
	v_exp_f32_e32 v3, v3
	s_nop 0
	v_add_f32_e32 v3, 1.0, v3
	v_rcp_f32_e32 v14, v3
	v_mul_f32_e32 v3, 0xbfb8aa3b, v13
	v_exp_f32_e32 v3, v3
	s_nop 0
	v_add_f32_e32 v3, 1.0, v3
	v_rcp_f32_e32 v15, v3
	s_nop 0
	v_pk_mul_f32 v[12:13], v[12:13], v[14:15]
	s_nop 0
	v_pk_mul_f32 v[12:13], v[88:89], v[12:13] op_sel_hi:[0,1]
	v_cvt_pk_f16_f32 v3, v12, v13
	ds_read_b128 v[38:41], v83 offset:2560
	ds_read_b128 v[12:15], v32 offset:1280
	ds_read_b128 v[34:37], v83 offset:4096
	ds_read_b128 v[16:19], v32 offset:2048
	ds_read_b128 v[28:31], v83 offset:5632
	ds_read_b128 v[24:27], v32 offset:2816
	s_waitcnt lgkmcnt(4)
; __device__ __forceinline__ void phase_dnprep(h16* Pdn, const h16* halo, const float* bd, const float* convw, const float* a_log, const float* dt_bias,
;                              h16* Tg, h16* qkg, float* gcg, float* betag, float* s2g, LAS unsigned char* ldsl, unsigned char* ldsb) {
;     ...
;                 for (int j = 0; j < 4; ++j) {
;                     const h16x8 x0 = *(const h16x8*)(raw + (i + j) * RP + seg * 128 + 16 * cp), x1 = *(const h16x8*)(raw + (i + j) * RP + seg * 128 + 16 * cp + 8);
;                     const f32x4* cwp = (const f32x4*)(cw + j * 384 + seg * 128 + 16 * cp);
;                     const f32x4 c0 = cwp[0], c1 = cwp[1], c2 = cwp[2], c3 = cwp[3];
; #pragma unroll
;                     for (int e = 0; e < 4; ++e) {
;                         y[e] += c0[e] * (float)x0[e]; y[4 + e] += c1[e] * (float)x0[4 + e];
;                         y[8 + e] += c2[e] * (float)x1[e]; y[12 + e] += c3[e] * (float)x1[4 + e];
;                     }
;                 }
; #pragma unroll
;                 for (int e = 0; e < 16; ++e) y[e] = silu_f(y[e]);
;                 float scl = bt_i;
;                 if (seg < 2) {
;                     float ss = 0.f;
; #pragma unroll
;                     for (int e = 0; e < 16; ++e) ss += y[e] * y[e];
;                     ss += shx(ss, 1, lane); ss += shx(ss, 2, lane); ss += shx(ss, 4, lane);
;                     scl = rsqrtf(ss + 1e-6f) * (seg == 0 ? 0.08838834764831845f : 1.0f);
;                 }
;                 h16x8 o0, o1;
; #pragma unroll
;                 for (int e = 0; e < 8; ++e) { o0[e] = (h16)(y[e] * scl); o1[e] = (h16)(y[8 + e] * scl); }
;                 if (seg == 0) { *(h16x8*)(qn + i * 136 + 16 * cp) = o0; *(h16x8*)(qn + i * 136 + 16 * cp + 8) = o1; }
;                 if (seg == 1) { *(h16x8*)(kn + i * 136 + 16 * cp) = o0; *(h16x8*)(kn + i * 136 + 16 * cp + 8) = o1; }
;                 gst((h16x8*)(gp + seg * 1024), o0); gst((h16x8*)(gp + seg * 1024 + 8), o1);
;             }
;         }
;         LDS_BARRIER();
; #pragma unroll
;         for (int idx0 = 0; idx0 < 4; ++idx0) {
;             const int idx = w + 8 * idx0;
;             const int isqk = idx >> 4, ti = (idx >> 2) & 3, tj = idx & 3;
;             f32x4 acc = {0.f, 0.f, 0.f, 0.f};
;             if (tj <= ti) {
;                 const h16* As = isqk ? qn : kn;
; #pragma unroll
;                 for (int kk = 0; kk < 4; ++kk) {
	v_cvt_f32_f16_e32 v42, v12
	v_cvt_f32_f16_sdwa v43, v12 dst_sel:DWORD dst_unused:UNUSED_PAD src0_sel:WORD_1
	v_cvt_f32_f16_e32 v12, v13
	v_cvt_f32_f16_sdwa v13, v13 dst_sel:DWORD dst_unused:UNUSED_PAD src0_sel:WORD_1
	v_pk_fma_f32 v[20:21], v[38:39], v[42:43], v[20:21]
	s_waitcnt lgkmcnt(2)
	v_cvt_f32_f16_e32 v38, v16
	v_cvt_f32_f16_sdwa v39, v16 dst_sel:DWORD dst_unused:UNUSED_PAD src0_sel:WORD_1
	v_cvt_f32_f16_e32 v16, v17
	v_cvt_f32_f16_sdwa v17, v17 dst_sel:DWORD dst_unused:UNUSED_PAD src0_sel:WORD_1
	v_pk_fma_f32 v[20:21], v[34:35], v[38:39], v[20:21]
	s_waitcnt lgkmcnt(0)
	v_cvt_f32_f16_e32 v34, v24
	v_cvt_f32_f16_sdwa v35, v24 dst_sel:DWORD dst_unused:UNUSED_PAD src0_sel:WORD_1
	v_cvt_f32_f16_e32 v38, v10
	v_cvt_f32_f16_sdwa v39, v10 dst_sel:DWORD dst_unused:UNUSED_PAD src0_sel:WORD_1
	v_cvt_f32_f16_e32 v24, v14
	v_pk_fma_f32 v[20:21], v[28:29], v[34:35], v[20:21]
	v_pk_fma_f32 v[4:5], v[4:5], v[38:39], 0 op_sel_hi:[1,1,0]
	v_mul_f32_e32 v8, 0xbfb8aa3b, v20
	v_exp_f32_e32 v8, v8
	s_nop 0
	v_add_f32_e32 v8, 1.0, v8
	v_rcp_f32_e32 v28, v8
	v_mul_f32_e32 v8, 0xbfb8aa3b, v21
	v_exp_f32_e32 v8, v8
	s_nop 0
	v_add_f32_e32 v8, 1.0, v8
	v_rcp_f32_e32 v29, v8
	s_nop 0
	v_pk_mul_f32 v[20:21], v[20:21], v[28:29]
	s_nop 0
	v_pk_mul_f32 v[20:21], v[88:89], v[20:21] op_sel_hi:[0,1]
	v_cvt_pk_f16_f32 v8, v20, v21
	v_cvt_f32_f16_e32 v20, v9
	v_cvt_f32_f16_sdwa v21, v9 dst_sel:DWORD dst_unused:UNUSED_PAD src0_sel:WORD_1
	v_pk_fma_f32 v[20:21], v[22:23], v[20:21], 0 op_sel_hi:[1,1,0]
	s_nop 0
	v_pk_fma_f32 v[12:13], v[40:41], v[12:13], v[20:21]
	s_nop 0
	v_pk_fma_f32 v[12:13], v[36:37], v[16:17], v[12:13]
	v_cvt_f32_f16_e32 v16, v25
	v_cvt_f32_f16_sdwa v17, v25 dst_sel:DWORD dst_unused:UNUSED_PAD src0_sel:WORD_1
	v_cvt_f32_f16_sdwa v25, v14 dst_sel:DWORD dst_unused:UNUSED_PAD src0_sel:WORD_1
	v_cvt_f32_f16_e32 v14, v15
	v_cvt_f32_f16_sdwa v15, v15 dst_sel:DWORD dst_unused:UNUSED_PAD src0_sel:WORD_1
	v_pk_fma_f32 v[12:13], v[30:31], v[16:17], v[12:13]
	ds_read_b128 v[20:23], v83 offset:5648
	ds_read_b128 v[28:31], v83 offset:4112
	ds_read_b128 v[34:37], v83 offset:2576
	v_mul_f32_e32 v9, 0xbfb8aa3b, v12
	v_exp_f32_e32 v9, v9
	s_waitcnt lgkmcnt(0)
	v_pk_fma_f32 v[4:5], v[34:35], v[24:25], v[4:5]
	v_add_f32_e32 v9, 1.0, v9
	v_rcp_f32_e32 v16, v9
	v_mul_f32_e32 v9, 0xbfb8aa3b, v13
	v_exp_f32_e32 v9, v9
	s_nop 0
	v_add_f32_e32 v9, 1.0, v9
	v_rcp_f32_e32 v17, v9
	s_nop 0
	v_pk_mul_f32 v[12:13], v[12:13], v[16:17]
	s_nop 0
	v_pk_mul_f32 v[12:13], v[88:89], v[12:13] op_sel_hi:[0,1]
	v_cvt_f32_f16_e32 v16, v18
	v_cvt_f32_f16_sdwa v17, v18 dst_sel:DWORD dst_unused:UNUSED_PAD src0_sel:WORD_1
	v_cvt_pk_f16_f32 v9, v12, v13
	v_cvt_f32_f16_e32 v12, v26
	v_cvt_f32_f16_sdwa v13, v26 dst_sel:DWORD dst_unused:UNUSED_PAD src0_sel:WORD_1
	v_pk_fma_f32 v[4:5], v[28:29], v[16:17], v[4:5]
	v_cvt_f32_f16_e32 v16, v11
	v_cvt_f32_f16_sdwa v17, v11 dst_sel:DWORD dst_unused:UNUSED_PAD src0_sel:WORD_1
	v_pk_fma_f32 v[4:5], v[20:21], v[12:13], v[4:5]
	v_pk_fma_f32 v[6:7], v[6:7], v[16:17], 0 op_sel_hi:[1,1,0]
	v_mul_f32_e32 v10, 0xbfb8aa3b, v4
	v_exp_f32_e32 v10, v10
	v_pk_fma_f32 v[6:7], v[36:37], v[14:15], v[6:7]
	v_add_f32_e32 v10, 1.0, v10
	v_rcp_f32_e32 v12, v10
	v_mul_f32_e32 v10, 0xbfb8aa3b, v5
	v_exp_f32_e32 v10, v10
	s_nop 0
	v_add_f32_e32 v10, 1.0, v10
	v_rcp_f32_e32 v13, v10
	s_nop 0
	v_pk_mul_f32 v[4:5], v[4:5], v[12:13]
	s_nop 0
	v_pk_mul_f32 v[4:5], v[88:89], v[4:5] op_sel_hi:[0,1]
	v_cvt_f32_f16_e32 v12, v19
	v_cvt_f32_f16_sdwa v13, v19 dst_sel:DWORD dst_unused:UNUSED_PAD src0_sel:WORD_1
	v_cvt_pk_f16_f32 v10, v4, v5
	v_cvt_f32_f16_e32 v4, v27
	v_cvt_f32_f16_sdwa v5, v27 dst_sel:DWORD dst_unused:UNUSED_PAD src0_sel:WORD_1
	v_pk_fma_f32 v[6:7], v[30:31], v[12:13], v[6:7]
	s_nop 0
	v_pk_fma_f32 v[4:5], v[22:23], v[4:5], v[6:7]
	s_nop 0
	v_mul_f32_e32 v6, 0xbfb8aa3b, v4
	v_mul_f32_e32 v7, 0xbfb8aa3b, v5
	v_exp_f32_e32 v6, v6
	v_exp_f32_e32 v7, v7
	v_or_b32_e32 v22, s76, v100
	v_add_f32_e32 v6, 1.0, v6
	v_add_f32_e32 v7, 1.0, v7
	v_rcp_f32_e32 v6, v6
	v_rcp_f32_e32 v7, v7
	s_nop 0
	v_pk_mul_f32 v[4:5], v[4:5], v[6:7]
	s_nop 0
	v_pk_mul_f32 v[4:5], v[88:89], v[4:5] op_sel_hi:[0,1]
	v_cvt_pk_f16_f32 v11, v4, v5
	v_add_co_u32_e32 v4, vcc, s1, v86
	s_nop 1
	v_addc_co_u32_e32 v5, vcc, 0, v87, vcc
	global_store_dwordx4 v[4:5], v[8:11], off
	global_store_dwordx4 v[4:5], v[0:3], off offset:16
	s_waitcnt lgkmcnt(0)
	s_barrier
	s_and_b64 vcc, exec, s[28:29]
	v_mul_u32_u24_e32 v0, 0x110, v22
	v_and_b32_e32 v2, 48, v99
	v_lshlrev_b32_e32 v1, 3, v84
	v_add3_u32 v23, s0, v0, v2
	v_or_b32_e32 v2, s95, v100
	v_mov_b32_e32 v0, 0
	v_lshlrev_b32_e32 v24, 1, v1
	v_mul_u32_u24_e32 v25, 0x110, v2
	v_mov_b32_e32 v1, 0
	v_mov_b32_e32 v2, 0
	v_mov_b32_e32 v3, 0
	s_cbranch_vccz .LBB0_356
	v_add3_u32 v12, s94, v25, v24
	ds_read_b128 v[0:3], v12
	ds_read_b128 v[4:7], v23
	s_waitcnt lgkmcnt(0)
	v_mfma_f32_16x16x32_f16 v[0:3], v[0:3], v[4:7], 0
	ds_read_b128 v[4:7], v12 offset:64
	ds_read_b128 v[8:11], v23 offset:64
	s_waitcnt lgkmcnt(0)
	v_mfma_f32_16x16x32_f16 v[0:3], v[4:7], v[8:11], v[0:3]
	ds_read_b128 v[4:7], v12 offset:128
	ds_read_b128 v[8:11], v23 offset:128
	s_waitcnt lgkmcnt(0)
	v_mfma_f32_16x16x32_f16 v[0:3], v[4:7], v[8:11], v[0:3]
	ds_read_b128 v[4:7], v12 offset:192
	ds_read_b128 v[8:11], v23 offset:192
	s_waitcnt lgkmcnt(0)
	v_mfma_f32_16x16x32_f16 v[0:3], v[4:7], v[8:11], v[0:3]

; #define LAUNDER_V(x) asm volatile("" : "+v"(x))
; #define LAUNDER_S(x) asm volatile("" : "+s"(x))
; __device__ __forceinline__ void phase_attn(const h16* Pda, h16* ob, float* lse, int pat, unsigned char* ldsb) {
;     int tid = threadIdx.x; LAUNDER_V(tid); int bid = blockIdx.x; LAUNDER_S(bid);
;     const int lane = tid & 63, w = __builtin_amdgcn_readfirstlane(tid >> 6), fr = lane & 15, g = lane >> 4;
;     const int r = (pat == 0) ? 1 : (pat == 1 ? 4 : 16);
;     const int nbk2 = 16 / r;
;     h16* Ks = (h16*)ldsb;
;     h16* Vs = Ks + 384 * 72;
;     h16* Qs = Vs + 384 * 72;
;     h16x8 pk[6], pv[6], pq[4];
;     ...
;     const int G_ = (int)gridDim.x;
;     if (bid < 1536) ATT_LOAD(bid);
.LBB0_432:
	v_readlane_b32 s0, v254, 63
	s_add_i32 s3, s0, -5
	s_cmp_lg_u32 s3, 0
	s_cselect_b64 s[0:1], -1, 0
	s_cmp_eq_u32 s3, 1
	s_cselect_b64 s[4:5], -1, 0
	s_and_b64 s[6:7], s[4:5], exec
	s_cselect_b32 s10, 4, 1
	s_cmp_eq_u32 s3, 0
	s_cselect_b64 s[6:7], -1, 0
	s_waitcnt vmcnt(0)
	v_mov_b32_e32 v99, v192
	s_mov_b32 s35, s52
	s_and_b64 s[8:9], s[6:7], exec
	s_cselect_b32 s75, 16, s10
	s_cmpk_lt_i32 s35, 0x600
	v_writelane_b32 v255, s0, 36
	s_cselect_b64 s[8:9], -1, 0
	s_cmpk_gt_i32 s35, 0x5ff
	v_readfirstlane_b32 s12, v99
	v_writelane_b32 v255, s1, 37
	s_cbranch_scc1 .LBB0_446
	s_and_b32 s10, s35, 7
	s_mulk_i32 s10, 0xc0
	s_ashr_i32 s11, s35, 3
	s_add_i32 s10, s10, s11
	s_mul_hi_i32 s11, s10, 0x2aaaaaab
	s_lshr_b32 s13, s11, 31
	s_ashr_i32 s11, s11, 5
	s_add_i32 s15, s11, s13
	s_mul_i32 s11, s15, 0xc0
	s_sub_i32 s10, s10, s11
	s_bfe_u32 s11, s10, 0x4001b
	s_sext_i32_i8 s13, s75
	s_add_i32 s11, s10, s11
	v_cvt_f32_i32_e32 v0, s13
	s_sext_i32_i16 s16, s11
	s_and_b32 s11, s11, 0xfff0
	s_sub_i32 s14, s10, s11
	s_sext_i32_i8 s10, s14
	v_cvt_f32_i32_e32 v1, s10
	v_rcp_iflag_f32_e32 v2, v0
	s_xor_b32 s10, s10, s13
	s_ashr_i32 s10, s10, 30
	s_or_b32 s13, s10, 1
	v_mul_f32_e32 v2, v1, v2
	v_trunc_f32_e32 v2, v2
	v_fma_f32 v1, -v2, v0, v1
	v_cvt_i32_f32_e32 v2, v2
	v_cmp_ge_f32_e64 s[10:11], |v1|, |v0|
	s_and_b64 s[10:11], s[10:11], exec
	s_cselect_b32 s10, s13, 0
	v_readfirstlane_b32 s11, v2
	s_add_i32 s10, s11, s10
	s_sext_i32_i8 s13, s10
	s_mul_i32 s10, s10, s75
	s_sub_i32 s10, s14, s10
	s_nop 0
	s_sext_i32_i8 s10, s10
	v_readlane_b32 s45, v254, 52
	s_lshl_b32 s14, s10, 8
	s_mov_b32 s21, s45
	s_mul_i32 s20, s15, 0x900000
	s_mov_b32 s17, s45
	s_nop 5
	v_readlane_b32 s43, v254, 50
	v_readlane_b32 s44, v254, 51
	v_readlane_b32 s46, v254, 53
	s_nop 0
	v_readlane_b32 s48, v254, 55
	v_readlane_b32 s49, v254, 56
	s_nop 1
	v_writelane_b32 v254, s8, 43
	v_mov_b32_e32 v44, v99
	v_mov_b32_e32 v2, v33
	v_writelane_b32 v254, s9, 44
	v_writelane_b32 v254, s10, 45
	v_writelane_b32 v254, s11, 46
	v_writelane_b32 v254, s12, 47
	v_writelane_b32 v254, s13, 48
	v_writelane_b32 v254, s14, 49
	v_writelane_b32 v254, s15, 50
	v_writelane_b32 v254, s16, 51
	v_writelane_b32 v254, s17, 52
	v_writelane_b32 v254, s18, 53
	v_writelane_b32 v254, s19, 54
	v_writelane_b32 v254, s20, 55
	v_writelane_b32 v254, s21, 56
	v_writelane_b32 v254, s22, 57
	v_writelane_b32 v254, s23, 58
	s_lshl_b64 s[10:11], s[20:21], 1
	s_add_u32 s15, s86, s10
	s_addc_u32 s17, s87, s11
	s_lshl_b32 s10, s16, 2
	s_andn2_b32 s10, s10, 63
	s_ashr_i32 s11, s10, 31
	s_lshl_b64 s[10:11], s[10:11], 1
	s_add_u32 s10, s15, s10
	s_addc_u32 s11, s17, s11
	s_add_i32 s16, s14, 0xffffff80
	s_and_b64 s[18:19], s[4:5], exec
	v_lshlrev_b32_e32 v0, 4, v44
	v_ashrrev_i32_e32 v52, 3, v44
	v_mov_b32_e32 v3, v33
	s_cselect_b32 s15, 2, 4
	s_and_b64 s[18:19], s[6:7], exec
	v_and_b32_e32 v32, 0x70, v0
	v_add_u32_e32 v12, s16, v52
	v_mov_b32_e32 v0, v33
	v_mov_b32_e32 v1, v33
	v_mov_b64_e32 v[10:11], v[2:3]
	v_mov_b64_e32 v[6:7], v[2:3]
	s_cselect_b32 s15, 0, s15
	v_lshl_add_u64 v[60:61], s[10:11], 0, v[32:33]
	v_cmp_lt_i32_e32 vcc, -1, v12
	v_mov_b64_e32 v[8:9], v[0:1]
	v_mov_b64_e32 v[4:5], v[0:1]
	s_and_saveexec_b64 s[10:11], vcc
	s_cbranch_execz .LBB0_435
	v_lshlrev_b32_e32 v4, s15, v12
	v_add_u32_e32 v4, s13, v4
	s_movk_i32 s17, 0x900
	v_mul_lo_u32 v32, v4, s17
	v_lshl_add_u64 v[4:5], v[32:33], 1, v[60:61]
	global_load_dwordx4 v[8:11], v[4:5], off offset:1536
	s_nop 0
	global_load_dwordx4 v[4:7], v[4:5], off offset:3072

; #define LAS __attribute__((address_space(3)))
; __device__ __forceinline__ float shx(float v, int m, int lane) { return __int_as_float(__builtin_amdgcn_ds_bpermute((lane ^ m) << 2, __float_as_int(v))); }
;     __device__ __forceinline__ void operator()(const f32x4 (&acc)[2][2][4][2], const Unit& u, int wr, int wc, int fr, int fq) const {
;         const int lane = fq * 16 + fr, wid = wr * 4 + wc, tid = wid * 64 + lane;
;         const int row0 = u.pm * BM + wr * 64 + fr, col0 = u.pn * BM + wc * 32 + 8 * fq;
;         const int b = (u.pm * BM) >> 12;
;         LAS float* red = (LAS float*)sm; LAS float* rs = red + 1024;
;         f32x4 gv[2][2];
; #pragma unroll
;         for (int bj = 0; bj < 2; ++bj)
; #pragma unroll
;             for (int n = 0; n < 2; ++n) gv[bj][n] = *(const f32x4*)(gate + b * 9216 + col0 + bj * HALF + 4 * n) * coef;
;         h16x8 ov[2][4][2];
; #pragma unroll
;         for (int ai = 0; ai < 2; ++ai)
; #pragma unroll
;             for (int m = 0; m < 4; ++m) {
;                 float sq = 0.f;
; #pragma unroll
;                 for (int bj = 0; bj < 2; ++bj) {
;                     const unsigned off = (unsigned)(row0 + ai * HALF + m * 16) * DM + col0 + bj * HALF;
;                     f32x4 xa, xb;
;                     if (F32IN) { xa = *(const f32x4*)(in32 + off); xb = *(const f32x4*)(in32 + off + 4); }
;                     else { const h16x8 xv = *(const h16x8*)(in16 + off); xa = (f32x4){(float)xv[0], (float)xv[1], (float)xv[2], (float)xv[3]}; xb = (f32x4){(float)xv[4], (float)xv[5], (float)xv[6], (float)xv[7]}; }
;                     h16x8 o;
; #pragma unroll
;                     for (int j = 0; j < 4; ++j) { o[j] = (h16)(xa[j] + gv[bj][0][j] * acc[ai][bj][m][0][j]); o[4 + j] = (h16)(xb[j] + gv[bj][1][j] * acc[ai][bj][m][1][j]); }
;                     if (!FINAL) *(h16x8*)(out + off) = o;
;                     ov[ai][m][bj] = o;
; #pragma unroll
;                     for (int j = 0; j < 8; ++j) sq += (float)o[j] * (float)o[j];
;                 }
;                 sq += shx(sq, 16, lane); sq += shx(sq, 32, lane);
;                 if (fq == 0) red[(ai * HALF + wr * 64 + m * 16 + fr) * 4 + wc] = sq;
;             }
.LBB0_567:
	s_lshl_b32 s24, s24, 8
	v_or_b32_e32 v150, s24, v179
	s_lshr_b32 s26, s73, 4
	v_lshl_add_u32 v148, s73, 18, v191
	v_add_u32_e32 v32, v148, v150
	s_nop 0
	s_mulk_i32 s26, 0x2400
	v_lshlrev_b64 v[160:161], 1, v[32:33]
	v_readlane_b32 s48, v253, 12
	v_readlane_b32 s49, v253, 13
	s_ashr_i32 s27, s26, 31
	s_lshl_b64 s[26:27], s[26:27], 2
	v_lshl_add_u64 v[176:177], s[48:49], 0, v[160:161]
	s_add_u32 s28, s94, s26
	s_addc_u32 s29, s95, s27
	v_ashrrev_i32_e32 v151, 31, v150
	v_lshl_add_u64 v[162:163], v[150:151], 2, s[28:29]
	global_load_dwordx4 v[156:159], v[162:163], off
	global_load_dwordx4 v[168:171], v[162:163], off offset:16
	v_mov_b32_e32 v139, v138
	v_lshl_add_u64 v[196:197], s[18:19], 0, v[160:161]
	global_load_dwordx4 v[172:175], v[162:163], off offset:512
	global_load_dwordx4 v[208:211], v[162:163], off offset:528
	v_lshlrev_b32_e32 v251, 1, v32
	v_add_u32_e32 v250, 0x0, v251
	global_load_dwordx4 v[218:221], v250, s[48:49]
	global_load_dwordx4 v[222:225], v250, s[48:49] offset:256
	v_add_u32_e32 v250, 0x8000, v251
	global_load_dwordx4 v[226:229], v250, s[48:49]
	global_load_dwordx4 v[230:233], v250, s[48:49] offset:256
	v_add_u32_e32 v250, 0x10000, v251
	global_load_dwordx4 v[234:237], v250, s[48:49]
	global_load_dwordx4 v[238:241], v250, s[48:49] offset:256
	v_add_u32_e32 v250, 0x18000, v251
	global_load_dwordx4 v[242:245], v250, s[48:49]
	global_load_dwordx4 v[246:249], v250, s[48:49] offset:256
	s_nop 7
	s_nop 4
	s_waitcnt vmcnt(7)
	v_cvt_f32_f16_e32 v198, v218
	v_cvt_f32_f16_sdwa v199, v218 dst_sel:DWORD dst_unused:UNUSED_PAD src0_sel:WORD_1
	v_cvt_f32_f16_e32 v152, v219
	v_cvt_f32_f16_sdwa v153, v219 dst_sel:DWORD dst_unused:UNUSED_PAD src0_sel:WORD_1
	v_cvt_f32_f16_e32 v212, v220
	v_cvt_f32_f16_sdwa v213, v220 dst_sel:DWORD dst_unused:UNUSED_PAD src0_sel:WORD_1
	v_cvt_f32_f16_e32 v154, v221
	v_cvt_f32_f16_sdwa v155, v221 dst_sel:DWORD dst_unused:UNUSED_PAD src0_sel:WORD_1
	s_waitcnt lgkmcnt(0)
	v_pk_mul_f32 v[164:165], v[158:159], v[138:139]
	v_pk_mul_f32 v[166:167], v[156:157], v[142:143]
	v_pk_mul_f32 v[160:161], v[138:139], v[170:171]
	v_pk_mul_f32 v[162:163], v[142:143], v[168:169]
	v_pk_fma_f32 v[126:127], v[126:127], v[166:167], v[198:199]
	v_pk_fma_f32 v[128:129], v[128:129], v[164:165], v[152:153]
	v_pk_fma_f32 v[122:123], v[122:123], v[162:163], v[212:213]
	v_pk_fma_f32 v[124:125], v[124:125], v[160:161], v[154:155]
	v_cvt_pk_f16_f32 v168, v126, v127
	v_cvt_pk_f16_f32 v169, v128, v129
	v_cvt_pk_f16_f32 v170, v122, v123
	v_cvt_pk_f16_f32 v171, v124, v125
	global_store_dwordx4 v[196:197], v[168:171], off
	v_cvt_f32_f16_e32 v124, v168
	v_cvt_f32_f16_sdwa v125, v168 dst_sel:DWORD dst_unused:UNUSED_PAD src0_sel:WORD_1
	v_cvt_f32_f16_e32 v122, v169
	v_cvt_f32_f16_sdwa v123, v169 dst_sel:DWORD dst_unused:UNUSED_PAD src0_sel:WORD_1
	v_cvt_f32_f16_e32 v128, v170
	v_cvt_f32_f16_sdwa v129, v170 dst_sel:DWORD dst_unused:UNUSED_PAD src0_sel:WORD_1
	v_pk_mul_f32 v[168:169], v[124:125], v[124:125]
	v_pk_mul_f32 v[156:157], v[138:139], v[174:175]
	v_pk_mul_f32 v[152:153], v[138:139], v[210:211]
	v_cvt_f32_f16_e32 v126, v171
	v_cvt_f32_f16_sdwa v127, v171 dst_sel:DWORD dst_unused:UNUSED_PAD src0_sel:WORD_1
	v_pk_mul_f32 v[170:171], v[122:123], v[122:123]
	v_add_f32_e32 v139, v168, v169
	v_add_f32_e32 v139, v170, v139
	v_add_f32_e32 v139, v171, v139
	v_pk_mul_f32 v[158:159], v[142:143], v[172:173]
	v_pk_mul_f32 v[172:173], v[128:129], v[128:129]
	v_pk_mul_f32 v[154:155], v[142:143], v[208:209]
	v_add_f32_e32 v139, v172, v139
	v_add_f32_e32 v139, v173, v139
	v_pk_mul_f32 v[174:175], v[126:127], v[126:127]
	s_waitcnt vmcnt(7)
	v_cvt_f32_f16_e32 v168, v222
	v_cvt_f32_f16_sdwa v169, v222 dst_sel:DWORD dst_unused:UNUSED_PAD src0_sel:WORD_1
	v_cvt_f32_f16_e32 v170, v223
	v_cvt_f32_f16_sdwa v171, v223 dst_sel:DWORD dst_unused:UNUSED_PAD src0_sel:WORD_1
	v_cvt_f32_f16_e32 v176, v225
	v_cvt_f32_f16_sdwa v177, v225 dst_sel:DWORD dst_unused:UNUSED_PAD src0_sel:WORD_1
	v_cvt_f32_f16_e32 v172, v224
	v_cvt_f32_f16_sdwa v173, v224 dst_sel:DWORD dst_unused:UNUSED_PAD src0_sel:WORD_1
	v_readlane_b32 s48, v253, 12
	v_readlane_b32 s49, v253, 13
	s_nop 4
	v_add_u32_e32 v250, 0x40000, v251
	global_load_dwordx4 v[218:221], v250, s[48:49]
	global_load_dwordx4 v[222:225], v250, s[48:49] offset:256
	v_pk_fma_f32 v[118:119], v[118:119], v[158:159], v[168:169]
	v_pk_fma_f32 v[120:121], v[120:121], v[156:157], v[170:171]
	v_cvt_pk_f16_f32 v168, v118, v119
	v_cvt_pk_f16_f32 v169, v120, v121
	v_cvt_f32_f16_e32 v120, v168
	v_cvt_f32_f16_sdwa v121, v168 dst_sel:DWORD dst_unused:UNUSED_PAD src0_sel:WORD_1
	v_pk_fma_f32 v[116:117], v[116:117], v[152:153], v[176:177]
	v_pk_fma_f32 v[114:115], v[114:115], v[154:155], v[172:173]
	v_cvt_pk_f16_f32 v171, v116, v117
	v_cvt_f32_f16_e32 v116, v169
	v_cvt_f32_f16_sdwa v117, v169 dst_sel:DWORD dst_unused:UNUSED_PAD src0_sel:WORD_1
	v_add_f32_e32 v139, v174, v139
	v_cvt_pk_f16_f32 v170, v114, v115
	v_cvt_f32_f16_e32 v118, v170
	v_cvt_f32_f16_sdwa v119, v170 dst_sel:DWORD dst_unused:UNUSED_PAD src0_sel:WORD_1
	v_pk_mul_f32 v[172:173], v[120:121], v[120:121]
	v_add_f32_e32 v139, v175, v139
	v_add_f32_e32 v139, v172, v139
	v_cvt_f32_f16_e32 v114, v171
	v_cvt_f32_f16_sdwa v115, v171 dst_sel:DWORD dst_unused:UNUSED_PAD src0_sel:WORD_1
	v_pk_mul_f32 v[176:177], v[116:117], v[116:117]
	v_add_f32_e32 v139, v173, v139
	v_add_f32_e32 v139, v176, v139
	v_pk_mul_f32 v[198:199], v[118:119], v[118:119]
	v_add_f32_e32 v139, v177, v139
	v_add_f32_e32 v139, v198, v139
	v_pk_mul_f32 v[208:209], v[114:115], v[114:115]
	v_add_f32_e32 v139, v199, v139
	v_add_f32_e32 v139, v208, v139
	v_add_f32_e32 v139, v209, v139
	ds_bpermute_b32 v149, v180, v139
	global_store_dwordx4 v[196:197], v[168:171], off offset:256
	s_waitcnt lgkmcnt(0)
	v_add_f32_e32 v139, v139, v149
	ds_bpermute_b32 v149, v181, v139
	s_and_saveexec_b64 s[28:29], s[4:5]
	s_cbranch_execz .LBB0_569
	s_waitcnt lgkmcnt(0)
	v_add_f32_e32 v139, v139, v149
	v_add_u32_e32 v149, s72, v190
	ds_write_b32 v149, v139
; #define LAS __attribute__((address_space(3)))
; __device__ __forceinline__ float shx(float v, int m, int lane) { return __int_as_float(__builtin_amdgcn_ds_bpermute((lane ^ m) << 2, __float_as_int(v))); }
;     __device__ __forceinline__ void operator()(const f32x4 (&acc)[2][2][4][2], const Unit& u, int wr, int wc, int fr, int fq) const {
;         const int lane = fq * 16 + fr, wid = wr * 4 + wc, tid = wid * 64 + lane;
;         const int row0 = u.pm * BM + wr * 64 + fr, col0 = u.pn * BM + wc * 32 + 8 * fq;
;         const int b = (u.pm * BM) >> 12;
;         LAS float* red = (LAS float*)sm; LAS float* rs = red + 1024;
;         f32x4 gv[2][2];
; #pragma unroll
;         for (int bj = 0; bj < 2; ++bj)
; #pragma unroll
;             for (int n = 0; n < 2; ++n) gv[bj][n] = *(const f32x4*)(gate + b * 9216 + col0 + bj * HALF + 4 * n) * coef;
;         h16x8 ov[2][4][2];
; #pragma unroll
;         for (int ai = 0; ai < 2; ++ai)
; #pragma unroll
;             for (int m = 0; m < 4; ++m) {
;                 float sq = 0.f;
; #pragma unroll
;                 for (int bj = 0; bj < 2; ++bj) {
;                     const unsigned off = (unsigned)(row0 + ai * HALF + m * 16) * DM + col0 + bj * HALF;
;                     f32x4 xa, xb;
;                     if (F32IN) { xa = *(const f32x4*)(in32 + off); xb = *(const f32x4*)(in32 + off + 4); }
;                     else { const h16x8 xv = *(const h16x8*)(in16 + off); xa = (f32x4){(float)xv[0], (float)xv[1], (float)xv[2], (float)xv[3]}; xb = (f32x4){(float)xv[4], (float)xv[5], (float)xv[6], (float)xv[7]}; }
;                     h16x8 o;
; #pragma unroll
;                     for (int j = 0; j < 4; ++j) { o[j] = (h16)(xa[j] + gv[bj][0][j] * acc[ai][bj][m][0][j]); o[4 + j] = (h16)(xb[j] + gv[bj][1][j] * acc[ai][bj][m][1][j]); }
;                     if (!FINAL) *(h16x8*)(out + off) = o;
;                     ov[ai][m][bj] = o;
; #pragma unroll
;                     for (int j = 0; j < 8; ++j) sq += (float)o[j] * (float)o[j];
;                 }
;                 sq += shx(sq, 16, lane); sq += shx(sq, 32, lane);
;                 if (fq == 0) red[(ai * HALF + wr * 64 + m * 16 + fr) * 4 + wc] = sq;
;             }
.LBB0_569:
	s_or_b64 exec, exec, s[28:29]
	v_add_u32_e32 v168, 0x4000, v32
	v_mov_b32_e32 v169, v33
	s_nop 0
	v_lshlrev_b64 v[172:173], 1, v[168:169]
	v_readlane_b32 s48, v253, 12
	v_readlane_b32 s49, v253, 13
	v_add_u32_e32 v174, 0x4080, v32
	v_mov_b32_e32 v175, v33
	v_lshl_add_u64 v[168:169], s[48:49], 0, v[172:173]
	v_lshlrev_b64 v[176:177], 1, v[174:175]
	v_lshl_add_u64 v[172:173], s[18:19], 0, v[172:173]
	v_lshl_add_u64 v[174:175], s[48:49], 0, v[176:177]
	s_nop 7
	s_nop 4
	s_waitcnt vmcnt(9)
	v_cvt_f32_f16_e32 v196, v226
	v_cvt_f32_f16_sdwa v197, v226 dst_sel:DWORD dst_unused:UNUSED_PAD src0_sel:WORD_1
	v_cvt_f32_f16_e32 v168, v227
	v_cvt_f32_f16_sdwa v169, v227 dst_sel:DWORD dst_unused:UNUSED_PAD src0_sel:WORD_1
	v_cvt_f32_f16_e32 v198, v228
	v_cvt_f32_f16_sdwa v199, v228 dst_sel:DWORD dst_unused:UNUSED_PAD src0_sel:WORD_1
	v_cvt_f32_f16_e32 v170, v229
	v_cvt_f32_f16_sdwa v171, v229 dst_sel:DWORD dst_unused:UNUSED_PAD src0_sel:WORD_1
	v_pk_fma_f32 v[110:111], v[110:111], v[166:167], v[196:197]
	v_pk_fma_f32 v[112:113], v[112:113], v[164:165], v[168:169]
	v_pk_fma_f32 v[106:107], v[106:107], v[162:163], v[198:199]
	v_pk_fma_f32 v[108:109], v[108:109], v[160:161], v[170:171]
	v_cvt_pk_f16_f32 v168, v110, v111
	v_cvt_pk_f16_f32 v169, v112, v113
	v_cvt_pk_f16_f32 v170, v106, v107
	v_cvt_pk_f16_f32 v171, v108, v109
	global_store_dwordx4 v[172:173], v[168:171], off
	v_cvt_f32_f16_e32 v108, v168
	v_cvt_f32_f16_sdwa v109, v168 dst_sel:DWORD dst_unused:UNUSED_PAD src0_sel:WORD_1
	v_cvt_f32_f16_e32 v106, v169
	v_cvt_f32_f16_sdwa v107, v169 dst_sel:DWORD dst_unused:UNUSED_PAD src0_sel:WORD_1
	v_cvt_f32_f16_e32 v112, v170
	v_pk_mul_f32 v[168:169], v[108:109], v[108:109]
	v_cvt_f32_f16_sdwa v113, v170 dst_sel:DWORD dst_unused:UNUSED_PAD src0_sel:WORD_1
	v_cvt_f32_f16_e32 v110, v171
	v_cvt_f32_f16_sdwa v111, v171 dst_sel:DWORD dst_unused:UNUSED_PAD src0_sel:WORD_1
	v_pk_mul_f32 v[170:171], v[106:107], v[106:107]
	v_add_f32_e32 v139, v168, v169
	v_add_f32_e32 v139, v170, v139
	v_add_f32_e32 v139, v171, v139
	v_pk_mul_f32 v[196:197], v[112:113], v[112:113]
	v_pk_mul_f32 v[198:199], v[110:111], v[110:111]
	v_add_f32_e32 v139, v196, v139
	v_add_f32_e32 v139, v197, v139
	v_add_f32_e32 v139, v198, v139
	v_add_f32_e32 v139, v199, v139
	s_waitcnt vmcnt(9)
	v_cvt_f32_f16_e32 v168, v230
	v_cvt_f32_f16_sdwa v169, v230 dst_sel:DWORD dst_unused:UNUSED_PAD src0_sel:WORD_1
	v_cvt_f32_f16_e32 v170, v231
	v_cvt_f32_f16_sdwa v171, v231 dst_sel:DWORD dst_unused:UNUSED_PAD src0_sel:WORD_1
	v_cvt_f32_f16_e32 v172, v232
	v_cvt_f32_f16_sdwa v173, v232 dst_sel:DWORD dst_unused:UNUSED_PAD src0_sel:WORD_1
	v_cvt_f32_f16_e32 v174, v233
	v_cvt_f32_f16_sdwa v175, v233 dst_sel:DWORD dst_unused:UNUSED_PAD src0_sel:WORD_1
	v_readlane_b32 s48, v253, 12
	v_readlane_b32 s49, v253, 13
	s_nop 4
	v_add_u32_e32 v250, 0x48000, v251
	global_load_dwordx4 v[226:229], v250, s[48:49]
	global_load_dwordx4 v[230:233], v250, s[48:49] offset:256
	v_pk_fma_f32 v[102:103], v[102:103], v[158:159], v[168:169]
	v_pk_fma_f32 v[104:105], v[104:105], v[156:157], v[170:171]
	v_cvt_pk_f16_f32 v168, v102, v103
	v_cvt_pk_f16_f32 v169, v104, v105
	v_cvt_f32_f16_e32 v104, v168
	v_cvt_f32_f16_sdwa v105, v168 dst_sel:DWORD dst_unused:UNUSED_PAD src0_sel:WORD_1
	v_pk_fma_f32 v[100:101], v[100:101], v[152:153], v[174:175]
	v_pk_fma_f32 v[98:99], v[98:99], v[154:155], v[172:173]
	v_cvt_pk_f16_f32 v171, v100, v101
	v_cvt_f32_f16_e32 v100, v169
	v_cvt_f32_f16_sdwa v101, v169 dst_sel:DWORD dst_unused:UNUSED_PAD src0_sel:WORD_1
	v_cvt_pk_f16_f32 v170, v98, v99
	v_cvt_f32_f16_e32 v102, v170
	v_cvt_f32_f16_sdwa v103, v170 dst_sel:DWORD dst_unused:UNUSED_PAD src0_sel:WORD_1
	v_pk_mul_f32 v[172:173], v[104:105], v[104:105]
	v_cvt_f32_f16_e32 v98, v171
	v_add_f32_e32 v139, v172, v139
	v_cvt_f32_f16_sdwa v99, v171 dst_sel:DWORD dst_unused:UNUSED_PAD src0_sel:WORD_1
	v_pk_mul_f32 v[174:175], v[100:101], v[100:101]
	v_add_f32_e32 v139, v173, v139
	v_add_f32_e32 v139, v174, v139
	v_pk_mul_f32 v[196:197], v[102:103], v[102:103]
	v_add_f32_e32 v139, v175, v139
	v_add_f32_e32 v139, v196, v139
	v_pk_mul_f32 v[208:209], v[98:99], v[98:99]
	v_add_f32_e32 v139, v197, v139
	v_add_f32_e32 v139, v208, v139
	v_add_f32_e32 v139, v209, v139
	s_waitcnt lgkmcnt(0)
	ds_bpermute_b32 v149, v180, v139
	v_lshl_add_u64 v[172:173], s[18:19], 0, v[176:177]
	global_store_dwordx4 v[172:173], v[168:171], off
	s_waitcnt lgkmcnt(0)
	v_add_f32_e32 v139, v139, v149
	ds_bpermute_b32 v149, v181, v139
	s_and_saveexec_b64 s[28:29], s[4:5]
	s_cbranch_execz .LBB0_571
	s_waitcnt lgkmcnt(0)
	v_add_f32_e32 v139, v139, v149
	v_add_u32_e32 v149, s72, v190
	ds_write_b32 v149, v139 offset:256
; #define LAS __attribute__((address_space(3)))
; __device__ __forceinline__ float shx(float v, int m, int lane) { return __int_as_float(__builtin_amdgcn_ds_bpermute((lane ^ m) << 2, __float_as_int(v))); }
;     __device__ __forceinline__ void operator()(const f32x4 (&acc)[2][2][4][2], const Unit& u, int wr, int wc, int fr, int fq) const {
;         const int lane = fq * 16 + fr, wid = wr * 4 + wc, tid = wid * 64 + lane;
;         const int row0 = u.pm * BM + wr * 64 + fr, col0 = u.pn * BM + wc * 32 + 8 * fq;
;         const int b = (u.pm * BM) >> 12;
;         LAS float* red = (LAS float*)sm; LAS float* rs = red + 1024;
;         f32x4 gv[2][2];
; #pragma unroll
;         for (int bj = 0; bj < 2; ++bj)
; #pragma unroll
;             for (int n = 0; n < 2; ++n) gv[bj][n] = *(const f32x4*)(gate + b * 9216 + col0 + bj * HALF + 4 * n) * coef;
;         h16x8 ov[2][4][2];
; #pragma unroll
;         for (int ai = 0; ai < 2; ++ai)
; #pragma unroll
;             for (int m = 0; m < 4; ++m) {
;                 float sq = 0.f;
; #pragma unroll
;                 for (int bj = 0; bj < 2; ++bj) {
;                     const unsigned off = (unsigned)(row0 + ai * HALF + m * 16) * DM + col0 + bj * HALF;
;                     f32x4 xa, xb;
;                     if (F32IN) { xa = *(const f32x4*)(in32 + off); xb = *(const f32x4*)(in32 + off + 4); }
;                     else { const h16x8 xv = *(const h16x8*)(in16 + off); xa = (f32x4){(float)xv[0], (float)xv[1], (float)xv[2], (float)xv[3]}; xb = (f32x4){(float)xv[4], (float)xv[5], (float)xv[6], (float)xv[7]}; }
;                     h16x8 o;
; #pragma unroll
;                     for (int j = 0; j < 4; ++j) { o[j] = (h16)(xa[j] + gv[bj][0][j] * acc[ai][bj][m][0][j]); o[4 + j] = (h16)(xb[j] + gv[bj][1][j] * acc[ai][bj][m][1][j]); }
;                     if (!FINAL) *(h16x8*)(out + off) = o;
;                     ov[ai][m][bj] = o;
; #pragma unroll
;                     for (int j = 0; j < 8; ++j) sq += (float)o[j] * (float)o[j];
;                 }
;                 sq += shx(sq, 16, lane); sq += shx(sq, 32, lane);
;                 if (fq == 0) red[(ai * HALF + wr * 64 + m * 16 + fr) * 4 + wc] = sq;
;             }
.LBB0_571:
	s_or_b64 exec, exec, s[28:29]
	v_add_u32_e32 v168, 0x8000, v32
	v_mov_b32_e32 v169, v33
	s_nop 0
	v_lshlrev_b64 v[172:173], 1, v[168:169]
	v_readlane_b32 s48, v253, 12
	v_readlane_b32 s49, v253, 13
	v_add_u32_e32 v174, 0x8080, v32
	v_mov_b32_e32 v175, v33
	v_lshl_add_u64 v[168:169], s[48:49], 0, v[172:173]
	v_lshlrev_b64 v[176:177], 1, v[174:175]
	v_lshl_add_u64 v[172:173], s[18:19], 0, v[172:173]
	v_lshl_add_u64 v[174:175], s[48:49], 0, v[176:177]
	s_nop 7
	s_nop 4
	s_waitcnt vmcnt(11)
	v_cvt_f32_f16_e32 v196, v234
	v_cvt_f32_f16_sdwa v197, v234 dst_sel:DWORD dst_unused:UNUSED_PAD src0_sel:WORD_1
	v_cvt_f32_f16_e32 v168, v235
	v_cvt_f32_f16_sdwa v169, v235 dst_sel:DWORD dst_unused:UNUSED_PAD src0_sel:WORD_1
	v_cvt_f32_f16_e32 v198, v236
	v_cvt_f32_f16_sdwa v199, v236 dst_sel:DWORD dst_unused:UNUSED_PAD src0_sel:WORD_1
	v_cvt_f32_f16_e32 v170, v237
	v_cvt_f32_f16_sdwa v171, v237 dst_sel:DWORD dst_unused:UNUSED_PAD src0_sel:WORD_1
	v_pk_fma_f32 v[94:95], v[94:95], v[166:167], v[196:197]
	v_pk_fma_f32 v[96:97], v[96:97], v[164:165], v[168:169]
	v_pk_fma_f32 v[90:91], v[90:91], v[162:163], v[198:199]
	v_pk_fma_f32 v[92:93], v[92:93], v[160:161], v[170:171]
	v_cvt_pk_f16_f32 v168, v94, v95
	v_cvt_pk_f16_f32 v169, v96, v97
	v_cvt_pk_f16_f32 v170, v90, v91
	v_cvt_pk_f16_f32 v171, v92, v93
	global_store_dwordx4 v[172:173], v[168:171], off
	v_cvt_f32_f16_e32 v92, v168
	v_cvt_f32_f16_sdwa v93, v168 dst_sel:DWORD dst_unused:UNUSED_PAD src0_sel:WORD_1
	v_cvt_f32_f16_e32 v90, v169
	v_cvt_f32_f16_sdwa v91, v169 dst_sel:DWORD dst_unused:UNUSED_PAD src0_sel:WORD_1
	v_cvt_f32_f16_e32 v96, v170
	v_pk_mul_f32 v[168:169], v[92:93], v[92:93]
	v_cvt_f32_f16_sdwa v97, v170 dst_sel:DWORD dst_unused:UNUSED_PAD src0_sel:WORD_1
	v_cvt_f32_f16_e32 v94, v171
	v_cvt_f32_f16_sdwa v95, v171 dst_sel:DWORD dst_unused:UNUSED_PAD src0_sel:WORD_1
	v_pk_mul_f32 v[170:171], v[90:91], v[90:91]
	v_add_f32_e32 v139, v168, v169
	v_add_f32_e32 v139, v170, v139
	v_add_f32_e32 v139, v171, v139
	v_pk_mul_f32 v[196:197], v[96:97], v[96:97]
	v_pk_mul_f32 v[198:199], v[94:95], v[94:95]
	v_add_f32_e32 v139, v196, v139
	v_add_f32_e32 v139, v197, v139
	v_add_f32_e32 v139, v198, v139
	v_add_f32_e32 v139, v199, v139
	s_waitcnt vmcnt(11)
	v_cvt_f32_f16_e32 v168, v238
	v_cvt_f32_f16_sdwa v169, v238 dst_sel:DWORD dst_unused:UNUSED_PAD src0_sel:WORD_1
	v_cvt_f32_f16_e32 v170, v239
	v_cvt_f32_f16_sdwa v171, v239 dst_sel:DWORD dst_unused:UNUSED_PAD src0_sel:WORD_1
	v_cvt_f32_f16_e32 v172, v240
	v_cvt_f32_f16_sdwa v173, v240 dst_sel:DWORD dst_unused:UNUSED_PAD src0_sel:WORD_1
	v_cvt_f32_f16_e32 v174, v241
	v_cvt_f32_f16_sdwa v175, v241 dst_sel:DWORD dst_unused:UNUSED_PAD src0_sel:WORD_1
	v_readlane_b32 s48, v253, 12
	v_readlane_b32 s49, v253, 13
	s_nop 4
	v_add_u32_e32 v250, 0x50000, v251
	global_load_dwordx4 v[234:237], v250, s[48:49]
	global_load_dwordx4 v[238:241], v250, s[48:49] offset:256
	v_pk_fma_f32 v[86:87], v[86:87], v[158:159], v[168:169]
	v_pk_fma_f32 v[88:89], v[88:89], v[156:157], v[170:171]
	v_cvt_pk_f16_f32 v168, v86, v87
	v_cvt_pk_f16_f32 v169, v88, v89
	v_cvt_f32_f16_e32 v88, v168
	v_cvt_f32_f16_sdwa v89, v168 dst_sel:DWORD dst_unused:UNUSED_PAD src0_sel:WORD_1
	v_pk_fma_f32 v[84:85], v[84:85], v[152:153], v[174:175]
	v_pk_fma_f32 v[82:83], v[82:83], v[154:155], v[172:173]
	v_cvt_pk_f16_f32 v171, v84, v85
	v_cvt_f32_f16_e32 v84, v169
	v_cvt_f32_f16_sdwa v85, v169 dst_sel:DWORD dst_unused:UNUSED_PAD src0_sel:WORD_1
	v_cvt_pk_f16_f32 v170, v82, v83
	v_cvt_f32_f16_e32 v86, v170
	v_cvt_f32_f16_sdwa v87, v170 dst_sel:DWORD dst_unused:UNUSED_PAD src0_sel:WORD_1
	v_pk_mul_f32 v[172:173], v[88:89], v[88:89]
	v_cvt_f32_f16_e32 v82, v171
	v_add_f32_e32 v139, v172, v139
	v_cvt_f32_f16_sdwa v83, v171 dst_sel:DWORD dst_unused:UNUSED_PAD src0_sel:WORD_1
	v_pk_mul_f32 v[174:175], v[84:85], v[84:85]
	v_add_f32_e32 v139, v173, v139
	v_add_f32_e32 v139, v174, v139
	v_pk_mul_f32 v[196:197], v[86:87], v[86:87]
	v_add_f32_e32 v139, v175, v139
	v_add_f32_e32 v139, v196, v139
	v_pk_mul_f32 v[208:209], v[82:83], v[82:83]
	v_add_f32_e32 v139, v197, v139
	v_add_f32_e32 v139, v208, v139
	v_add_f32_e32 v139, v209, v139
	s_waitcnt lgkmcnt(0)
	ds_bpermute_b32 v149, v180, v139
	v_lshl_add_u64 v[172:173], s[18:19], 0, v[176:177]
	global_store_dwordx4 v[172:173], v[168:171], off
	s_waitcnt lgkmcnt(0)
	v_add_f32_e32 v139, v139, v149
	ds_bpermute_b32 v149, v181, v139
	s_and_saveexec_b64 s[28:29], s[4:5]
	s_cbranch_execz .LBB0_573
	s_waitcnt lgkmcnt(0)
	v_add_f32_e32 v139, v139, v149
	v_add_u32_e32 v149, s72, v190
	ds_write_b32 v149, v139 offset:512
; #define LAS __attribute__((address_space(3)))
; __device__ __forceinline__ float shx(float v, int m, int lane) { return __int_as_float(__builtin_amdgcn_ds_bpermute((lane ^ m) << 2, __float_as_int(v))); }
;     __device__ __forceinline__ void operator()(const f32x4 (&acc)[2][2][4][2], const Unit& u, int wr, int wc, int fr, int fq) const {
;         const int lane = fq * 16 + fr, wid = wr * 4 + wc, tid = wid * 64 + lane;
;         const int row0 = u.pm * BM + wr * 64 + fr, col0 = u.pn * BM + wc * 32 + 8 * fq;
;         const int b = (u.pm * BM) >> 12;
;         LAS float* red = (LAS float*)sm; LAS float* rs = red + 1024;
;         f32x4 gv[2][2];
; #pragma unroll
;         for (int bj = 0; bj < 2; ++bj)
; #pragma unroll
;             for (int n = 0; n < 2; ++n) gv[bj][n] = *(const f32x4*)(gate + b * 9216 + col0 + bj * HALF + 4 * n) * coef;
;         h16x8 ov[2][4][2];
; #pragma unroll
;         for (int ai = 0; ai < 2; ++ai)
; #pragma unroll
;             for (int m = 0; m < 4; ++m) {
;                 float sq = 0.f;
; #pragma unroll
;                 for (int bj = 0; bj < 2; ++bj) {
;                     const unsigned off = (unsigned)(row0 + ai * HALF + m * 16) * DM + col0 + bj * HALF;
;                     f32x4 xa, xb;
;                     if (F32IN) { xa = *(const f32x4*)(in32 + off); xb = *(const f32x4*)(in32 + off + 4); }
;                     else { const h16x8 xv = *(const h16x8*)(in16 + off); xa = (f32x4){(float)xv[0], (float)xv[1], (float)xv[2], (float)xv[3]}; xb = (f32x4){(float)xv[4], (float)xv[5], (float)xv[6], (float)xv[7]}; }
;                     h16x8 o;
; #pragma unroll
;                     for (int j = 0; j < 4; ++j) { o[j] = (h16)(xa[j] + gv[bj][0][j] * acc[ai][bj][m][0][j]); o[4 + j] = (h16)(xb[j] + gv[bj][1][j] * acc[ai][bj][m][1][j]); }
;                     if (!FINAL) *(h16x8*)(out + off) = o;
;                     ov[ai][m][bj] = o;
; #pragma unroll
;                     for (int j = 0; j < 8; ++j) sq += (float)o[j] * (float)o[j];
;                 }
;                 sq += shx(sq, 16, lane); sq += shx(sq, 32, lane);
;                 if (fq == 0) red[(ai * HALF + wr * 64 + m * 16 + fr) * 4 + wc] = sq;
;             }
.LBB0_573:
	s_or_b64 exec, exec, s[28:29]
	v_add_u32_e32 v168, 0xc000, v32
	v_mov_b32_e32 v169, v33
	s_nop 0
	v_lshlrev_b64 v[172:173], 1, v[168:169]
	v_readlane_b32 s48, v253, 12
	v_readlane_b32 s49, v253, 13
	v_add_u32_e32 v174, 0xc080, v32
	v_mov_b32_e32 v175, v33
	v_lshl_add_u64 v[168:169], s[48:49], 0, v[172:173]
	v_lshlrev_b64 v[176:177], 1, v[174:175]
	v_lshl_add_u64 v[172:173], s[18:19], 0, v[172:173]
	v_lshl_add_u64 v[174:175], s[48:49], 0, v[176:177]
	s_nop 7
	s_nop 4
	s_waitcnt vmcnt(13)
	v_cvt_f32_f16_e32 v196, v242
	v_cvt_f32_f16_sdwa v197, v242 dst_sel:DWORD dst_unused:UNUSED_PAD src0_sel:WORD_1
	v_cvt_f32_f16_e32 v168, v243
	v_cvt_f32_f16_sdwa v169, v243 dst_sel:DWORD dst_unused:UNUSED_PAD src0_sel:WORD_1
	v_cvt_f32_f16_e32 v198, v244
	v_cvt_f32_f16_sdwa v199, v244 dst_sel:DWORD dst_unused:UNUSED_PAD src0_sel:WORD_1
	v_cvt_f32_f16_e32 v170, v245
	v_cvt_f32_f16_sdwa v171, v245 dst_sel:DWORD dst_unused:UNUSED_PAD src0_sel:WORD_1
	v_pk_fma_f32 v[78:79], v[78:79], v[166:167], v[196:197]
	v_pk_fma_f32 v[80:81], v[80:81], v[164:165], v[168:169]
	v_pk_fma_f32 v[74:75], v[74:75], v[162:163], v[198:199]
	v_pk_fma_f32 v[76:77], v[76:77], v[160:161], v[170:171]
	v_cvt_pk_f16_f32 v168, v78, v79
	v_cvt_pk_f16_f32 v169, v80, v81
	v_cvt_pk_f16_f32 v170, v74, v75
	v_cvt_pk_f16_f32 v171, v76, v77
	global_store_dwordx4 v[172:173], v[168:171], off
	v_cvt_f32_f16_e32 v76, v168
	v_cvt_f32_f16_sdwa v77, v168 dst_sel:DWORD dst_unused:UNUSED_PAD src0_sel:WORD_1
	v_cvt_f32_f16_e32 v74, v169
	v_cvt_f32_f16_sdwa v75, v169 dst_sel:DWORD dst_unused:UNUSED_PAD src0_sel:WORD_1
	v_cvt_f32_f16_e32 v80, v170
	v_pk_mul_f32 v[168:169], v[76:77], v[76:77]
	v_cvt_f32_f16_sdwa v81, v170 dst_sel:DWORD dst_unused:UNUSED_PAD src0_sel:WORD_1
	v_cvt_f32_f16_e32 v78, v171
	v_cvt_f32_f16_sdwa v79, v171 dst_sel:DWORD dst_unused:UNUSED_PAD src0_sel:WORD_1
	v_pk_mul_f32 v[170:171], v[74:75], v[74:75]
	v_add_f32_e32 v139, v168, v169
	v_add_f32_e32 v139, v170, v139
	v_add_f32_e32 v139, v171, v139
	v_pk_mul_f32 v[196:197], v[80:81], v[80:81]
	v_pk_mul_f32 v[198:199], v[78:79], v[78:79]
	v_add_f32_e32 v139, v196, v139
	v_add_f32_e32 v139, v197, v139
	v_add_f32_e32 v139, v198, v139
	v_add_f32_e32 v139, v199, v139
	s_waitcnt vmcnt(13)
	v_cvt_f32_f16_e32 v168, v246
	v_cvt_f32_f16_sdwa v169, v246 dst_sel:DWORD dst_unused:UNUSED_PAD src0_sel:WORD_1
	v_cvt_f32_f16_e32 v170, v247
	v_cvt_f32_f16_sdwa v171, v247 dst_sel:DWORD dst_unused:UNUSED_PAD src0_sel:WORD_1
	v_cvt_f32_f16_e32 v172, v248
	v_cvt_f32_f16_sdwa v173, v248 dst_sel:DWORD dst_unused:UNUSED_PAD src0_sel:WORD_1
	v_cvt_f32_f16_e32 v174, v249
	v_cvt_f32_f16_sdwa v175, v249 dst_sel:DWORD dst_unused:UNUSED_PAD src0_sel:WORD_1
	v_readlane_b32 s48, v253, 12
	v_readlane_b32 s49, v253, 13
	s_nop 4
	v_add_u32_e32 v250, 0x58000, v251
	global_load_dwordx4 v[242:245], v250, s[48:49]
	global_load_dwordx4 v[246:249], v250, s[48:49] offset:256
	v_pk_fma_f32 v[70:71], v[70:71], v[158:159], v[168:169]
	v_pk_fma_f32 v[72:73], v[72:73], v[156:157], v[170:171]
	v_cvt_pk_f16_f32 v168, v70, v71
	v_cvt_pk_f16_f32 v169, v72, v73
	v_cvt_f32_f16_e32 v72, v168
	v_cvt_f32_f16_sdwa v73, v168 dst_sel:DWORD dst_unused:UNUSED_PAD src0_sel:WORD_1
	v_pk_fma_f32 v[68:69], v[68:69], v[152:153], v[174:175]
	v_pk_fma_f32 v[66:67], v[66:67], v[154:155], v[172:173]
	v_cvt_pk_f16_f32 v171, v68, v69
	v_cvt_f32_f16_e32 v68, v169
	v_cvt_f32_f16_sdwa v69, v169 dst_sel:DWORD dst_unused:UNUSED_PAD src0_sel:WORD_1
	v_cvt_pk_f16_f32 v170, v66, v67
	v_cvt_f32_f16_e32 v70, v170
	v_cvt_f32_f16_sdwa v71, v170 dst_sel:DWORD dst_unused:UNUSED_PAD src0_sel:WORD_1
	v_pk_mul_f32 v[172:173], v[72:73], v[72:73]
	v_cvt_f32_f16_e32 v66, v171
	v_add_f32_e32 v139, v172, v139
	v_cvt_f32_f16_sdwa v67, v171 dst_sel:DWORD dst_unused:UNUSED_PAD src0_sel:WORD_1
	v_pk_mul_f32 v[174:175], v[68:69], v[68:69]
	v_add_f32_e32 v139, v173, v139
	v_add_f32_e32 v139, v174, v139
	v_pk_mul_f32 v[196:197], v[70:71], v[70:71]
	v_add_f32_e32 v139, v175, v139
	v_add_f32_e32 v139, v196, v139
	v_pk_mul_f32 v[208:209], v[66:67], v[66:67]
	v_add_f32_e32 v139, v197, v139
	v_add_f32_e32 v139, v208, v139
	v_add_f32_e32 v139, v209, v139
	s_waitcnt lgkmcnt(0)
	ds_bpermute_b32 v149, v180, v139
	v_lshl_add_u64 v[172:173], s[18:19], 0, v[176:177]
	global_store_dwordx4 v[172:173], v[168:171], off
	s_waitcnt lgkmcnt(0)
	v_add_f32_e32 v139, v139, v149
	ds_bpermute_b32 v149, v181, v139
	s_and_saveexec_b64 s[28:29], s[4:5]
	s_cbranch_execz .LBB0_575
	s_waitcnt lgkmcnt(0)
	v_add_f32_e32 v139, v139, v149
	v_add_u32_e32 v149, s72, v190
	ds_write_b32 v149, v139 offset:768
; #define LAS __attribute__((address_space(3)))
; __device__ __forceinline__ float shx(float v, int m, int lane) { return __int_as_float(__builtin_amdgcn_ds_bpermute((lane ^ m) << 2, __float_as_int(v))); }
;     __device__ __forceinline__ void operator()(const f32x4 (&acc)[2][2][4][2], const Unit& u, int wr, int wc, int fr, int fq) const {
;         const int lane = fq * 16 + fr, wid = wr * 4 + wc, tid = wid * 64 + lane;
;         const int row0 = u.pm * BM + wr * 64 + fr, col0 = u.pn * BM + wc * 32 + 8 * fq;
;         const int b = (u.pm * BM) >> 12;
;         LAS float* red = (LAS float*)sm; LAS float* rs = red + 1024;
;         f32x4 gv[2][2];
; #pragma unroll
;         for (int bj = 0; bj < 2; ++bj)
; #pragma unroll
;             for (int n = 0; n < 2; ++n) gv[bj][n] = *(const f32x4*)(gate + b * 9216 + col0 + bj * HALF + 4 * n) * coef;
;         h16x8 ov[2][4][2];
; #pragma unroll
;         for (int ai = 0; ai < 2; ++ai)
; #pragma unroll
;             for (int m = 0; m < 4; ++m) {
;                 float sq = 0.f;
; #pragma unroll
;                 for (int bj = 0; bj < 2; ++bj) {
;                     const unsigned off = (unsigned)(row0 + ai * HALF + m * 16) * DM + col0 + bj * HALF;
;                     f32x4 xa, xb;
;                     if (F32IN) { xa = *(const f32x4*)(in32 + off); xb = *(const f32x4*)(in32 + off + 4); }
;                     else { const h16x8 xv = *(const h16x8*)(in16 + off); xa = (f32x4){(float)xv[0], (float)xv[1], (float)xv[2], (float)xv[3]}; xb = (f32x4){(float)xv[4], (float)xv[5], (float)xv[6], (float)xv[7]}; }
;                     h16x8 o;
; #pragma unroll
;                     for (int j = 0; j < 4; ++j) { o[j] = (h16)(xa[j] + gv[bj][0][j] * acc[ai][bj][m][0][j]); o[4 + j] = (h16)(xb[j] + gv[bj][1][j] * acc[ai][bj][m][1][j]); }
;                     if (!FINAL) *(h16x8*)(out + off) = o;
;                     ov[ai][m][bj] = o;
; #pragma unroll
;                     for (int j = 0; j < 8; ++j) sq += (float)o[j] * (float)o[j];
;                 }
;                 sq += shx(sq, 16, lane); sq += shx(sq, 32, lane);
;                 if (fq == 0) red[(ai * HALF + wr * 64 + m * 16 + fr) * 4 + wc] = sq;
;             }
.LBB0_575:
	s_or_b64 exec, exec, s[28:29]
	v_add_u32_e32 v168, 0x20000, v32
	v_mov_b32_e32 v169, v33
	s_nop 0
	v_lshlrev_b64 v[172:173], 1, v[168:169]
	v_readlane_b32 s48, v253, 12
	v_readlane_b32 s49, v253, 13
	v_add_u32_e32 v174, 0x20080, v32
	v_mov_b32_e32 v175, v33
	v_lshl_add_u64 v[168:169], s[48:49], 0, v[172:173]
	v_lshlrev_b64 v[176:177], 1, v[174:175]
	v_lshl_add_u64 v[172:173], s[18:19], 0, v[172:173]
	v_lshl_add_u64 v[174:175], s[48:49], 0, v[176:177]
	s_nop 7
	s_nop 4
	s_waitcnt vmcnt(14)
	v_cvt_f32_f16_e32 v196, v218
	v_cvt_f32_f16_sdwa v197, v218 dst_sel:DWORD dst_unused:UNUSED_PAD src0_sel:WORD_1
	v_cvt_f32_f16_e32 v168, v219
	v_cvt_f32_f16_sdwa v169, v219 dst_sel:DWORD dst_unused:UNUSED_PAD src0_sel:WORD_1
	v_cvt_f32_f16_e32 v198, v220
	v_cvt_f32_f16_sdwa v199, v220 dst_sel:DWORD dst_unused:UNUSED_PAD src0_sel:WORD_1
	v_cvt_f32_f16_e32 v170, v221
	v_cvt_f32_f16_sdwa v171, v221 dst_sel:DWORD dst_unused:UNUSED_PAD src0_sel:WORD_1
	v_pk_fma_f32 v[62:63], v[62:63], v[166:167], v[196:197]
	v_pk_fma_f32 v[64:65], v[64:65], v[164:165], v[168:169]
	v_pk_fma_f32 v[58:59], v[58:59], v[162:163], v[198:199]
	v_pk_fma_f32 v[60:61], v[60:61], v[160:161], v[170:171]
	v_cvt_pk_f16_f32 v168, v62, v63
	v_cvt_pk_f16_f32 v169, v64, v65
	v_cvt_pk_f16_f32 v170, v58, v59
	v_cvt_pk_f16_f32 v171, v60, v61
	global_store_dwordx4 v[172:173], v[168:171], off
	v_cvt_f32_f16_e32 v60, v168
	v_cvt_f32_f16_sdwa v61, v168 dst_sel:DWORD dst_unused:UNUSED_PAD src0_sel:WORD_1
	v_cvt_f32_f16_e32 v58, v169
	v_cvt_f32_f16_sdwa v59, v169 dst_sel:DWORD dst_unused:UNUSED_PAD src0_sel:WORD_1
	v_cvt_f32_f16_e32 v64, v170
	v_pk_mul_f32 v[168:169], v[60:61], v[60:61]
	v_cvt_f32_f16_sdwa v65, v170 dst_sel:DWORD dst_unused:UNUSED_PAD src0_sel:WORD_1
	v_cvt_f32_f16_e32 v62, v171
	v_cvt_f32_f16_sdwa v63, v171 dst_sel:DWORD dst_unused:UNUSED_PAD src0_sel:WORD_1
	v_pk_mul_f32 v[170:171], v[58:59], v[58:59]
	v_add_f32_e32 v139, v168, v169
	v_add_f32_e32 v139, v170, v139
	v_add_f32_e32 v139, v171, v139
	v_pk_mul_f32 v[196:197], v[64:65], v[64:65]
	v_pk_mul_f32 v[198:199], v[62:63], v[62:63]
	v_add_f32_e32 v139, v196, v139
	v_add_f32_e32 v139, v197, v139
	v_add_f32_e32 v139, v198, v139
	v_add_f32_e32 v139, v199, v139
	s_waitcnt vmcnt(14)
	v_cvt_f32_f16_e32 v168, v222
	v_cvt_f32_f16_sdwa v169, v222 dst_sel:DWORD dst_unused:UNUSED_PAD src0_sel:WORD_1
	v_cvt_f32_f16_e32 v170, v223
	v_cvt_f32_f16_sdwa v171, v223 dst_sel:DWORD dst_unused:UNUSED_PAD src0_sel:WORD_1
	v_cvt_f32_f16_e32 v172, v224
	v_cvt_f32_f16_sdwa v173, v224 dst_sel:DWORD dst_unused:UNUSED_PAD src0_sel:WORD_1
	v_cvt_f32_f16_e32 v174, v225
	v_cvt_f32_f16_sdwa v175, v225 dst_sel:DWORD dst_unused:UNUSED_PAD src0_sel:WORD_1
	v_pk_fma_f32 v[54:55], v[54:55], v[158:159], v[168:169]
	v_pk_fma_f32 v[56:57], v[56:57], v[156:157], v[170:171]
	v_cvt_pk_f16_f32 v168, v54, v55
	v_cvt_pk_f16_f32 v169, v56, v57
	v_cvt_f32_f16_e32 v56, v168
	v_cvt_f32_f16_sdwa v57, v168 dst_sel:DWORD dst_unused:UNUSED_PAD src0_sel:WORD_1
	v_pk_fma_f32 v[52:53], v[52:53], v[152:153], v[174:175]
	v_pk_fma_f32 v[50:51], v[50:51], v[154:155], v[172:173]
	v_cvt_pk_f16_f32 v171, v52, v53
	v_cvt_f32_f16_e32 v52, v169
	v_cvt_f32_f16_sdwa v53, v169 dst_sel:DWORD dst_unused:UNUSED_PAD src0_sel:WORD_1
	v_cvt_pk_f16_f32 v170, v50, v51
	v_cvt_f32_f16_e32 v54, v170
	v_cvt_f32_f16_sdwa v55, v170 dst_sel:DWORD dst_unused:UNUSED_PAD src0_sel:WORD_1
	v_pk_mul_f32 v[172:173], v[56:57], v[56:57]
	v_cvt_f32_f16_e32 v50, v171
	v_add_f32_e32 v139, v172, v139
	v_cvt_f32_f16_sdwa v51, v171 dst_sel:DWORD dst_unused:UNUSED_PAD src0_sel:WORD_1
	v_pk_mul_f32 v[174:175], v[52:53], v[52:53]
	v_add_f32_e32 v139, v173, v139
	v_add_f32_e32 v139, v174, v139
	v_pk_mul_f32 v[196:197], v[54:55], v[54:55]
	v_add_f32_e32 v139, v175, v139
	v_add_f32_e32 v139, v196, v139
	v_pk_mul_f32 v[208:209], v[50:51], v[50:51]
	v_add_f32_e32 v139, v197, v139
	v_add_f32_e32 v139, v208, v139
	v_add_f32_e32 v139, v209, v139
	s_waitcnt lgkmcnt(0)
	ds_bpermute_b32 v149, v180, v139
	v_lshl_add_u64 v[172:173], s[18:19], 0, v[176:177]
	global_store_dwordx4 v[172:173], v[168:171], off
	s_waitcnt lgkmcnt(0)
	v_add_f32_e32 v139, v139, v149
	ds_bpermute_b32 v149, v181, v139
	s_and_saveexec_b64 s[28:29], s[4:5]
	s_cbranch_execz .LBB0_577
	s_waitcnt lgkmcnt(0)
	v_add_f32_e32 v139, v139, v149
	v_add_u32_e32 v149, s72, v190
	ds_write_b32 v149, v139 offset:2048
; #define LAS __attribute__((address_space(3)))
; __device__ __forceinline__ float shx(float v, int m, int lane) { return __int_as_float(__builtin_amdgcn_ds_bpermute((lane ^ m) << 2, __float_as_int(v))); }
;     __device__ __forceinline__ void operator()(const f32x4 (&acc)[2][2][4][2], const Unit& u, int wr, int wc, int fr, int fq) const {
;         const int lane = fq * 16 + fr, wid = wr * 4 + wc, tid = wid * 64 + lane;
;         const int row0 = u.pm * BM + wr * 64 + fr, col0 = u.pn * BM + wc * 32 + 8 * fq;
;         const int b = (u.pm * BM) >> 12;
;         LAS float* red = (LAS float*)sm; LAS float* rs = red + 1024;
;         f32x4 gv[2][2];
; #pragma unroll
;         for (int bj = 0; bj < 2; ++bj)
; #pragma unroll
;             for (int n = 0; n < 2; ++n) gv[bj][n] = *(const f32x4*)(gate + b * 9216 + col0 + bj * HALF + 4 * n) * coef;
;         h16x8 ov[2][4][2];
; #pragma unroll
;         for (int ai = 0; ai < 2; ++ai)
; #pragma unroll
;             for (int m = 0; m < 4; ++m) {
;                 float sq = 0.f;
; #pragma unroll
;                 for (int bj = 0; bj < 2; ++bj) {
;                     const unsigned off = (unsigned)(row0 + ai * HALF + m * 16) * DM + col0 + bj * HALF;
;                     f32x4 xa, xb;
;                     if (F32IN) { xa = *(const f32x4*)(in32 + off); xb = *(const f32x4*)(in32 + off + 4); }
;                     else { const h16x8 xv = *(const h16x8*)(in16 + off); xa = (f32x4){(float)xv[0], (float)xv[1], (float)xv[2], (float)xv[3]}; xb = (f32x4){(float)xv[4], (float)xv[5], (float)xv[6], (float)xv[7]}; }
;                     h16x8 o;
; #pragma unroll
;                     for (int j = 0; j < 4; ++j) { o[j] = (h16)(xa[j] + gv[bj][0][j] * acc[ai][bj][m][0][j]); o[4 + j] = (h16)(xb[j] + gv[bj][1][j] * acc[ai][bj][m][1][j]); }
;                     if (!FINAL) *(h16x8*)(out + off) = o;
;                     ov[ai][m][bj] = o;
; #pragma unroll
;                     for (int j = 0; j < 8; ++j) sq += (float)o[j] * (float)o[j];
;                 }
;                 sq += shx(sq, 16, lane); sq += shx(sq, 32, lane);
;                 if (fq == 0) red[(ai * HALF + wr * 64 + m * 16 + fr) * 4 + wc] = sq;
;             }
.LBB0_577:
	s_or_b64 exec, exec, s[28:29]
	v_add_u32_e32 v168, 0x24000, v32
	v_mov_b32_e32 v169, v33
	s_nop 0
	v_lshlrev_b64 v[172:173], 1, v[168:169]
	v_readlane_b32 s48, v253, 12
	v_readlane_b32 s49, v253, 13
	v_add_u32_e32 v174, 0x24080, v32
	v_mov_b32_e32 v175, v33
	v_lshl_add_u64 v[168:169], s[48:49], 0, v[172:173]
	v_lshlrev_b64 v[176:177], 1, v[174:175]
	v_lshl_add_u64 v[172:173], s[18:19], 0, v[172:173]
	v_lshl_add_u64 v[174:175], s[48:49], 0, v[176:177]
	s_nop 7
	s_nop 4
	s_waitcnt vmcnt(12)
	v_cvt_f32_f16_e32 v196, v226
	v_cvt_f32_f16_sdwa v197, v226 dst_sel:DWORD dst_unused:UNUSED_PAD src0_sel:WORD_1
	v_cvt_f32_f16_e32 v168, v227
	v_cvt_f32_f16_sdwa v169, v227 dst_sel:DWORD dst_unused:UNUSED_PAD src0_sel:WORD_1
	v_cvt_f32_f16_e32 v198, v228
	v_cvt_f32_f16_sdwa v199, v228 dst_sel:DWORD dst_unused:UNUSED_PAD src0_sel:WORD_1
	v_cvt_f32_f16_e32 v170, v229
	v_cvt_f32_f16_sdwa v171, v229 dst_sel:DWORD dst_unused:UNUSED_PAD src0_sel:WORD_1
	v_pk_fma_f32 v[46:47], v[46:47], v[166:167], v[196:197]
	v_pk_fma_f32 v[48:49], v[48:49], v[164:165], v[168:169]
	v_pk_fma_f32 v[42:43], v[42:43], v[162:163], v[198:199]
	v_pk_fma_f32 v[44:45], v[44:45], v[160:161], v[170:171]
	v_cvt_pk_f16_f32 v168, v46, v47
	v_cvt_pk_f16_f32 v169, v48, v49
	v_cvt_pk_f16_f32 v170, v42, v43
	v_cvt_pk_f16_f32 v171, v44, v45
	global_store_dwordx4 v[172:173], v[168:171], off
	v_cvt_f32_f16_e32 v48, v168
	v_cvt_f32_f16_sdwa v49, v168 dst_sel:DWORD dst_unused:UNUSED_PAD src0_sel:WORD_1
	v_cvt_f32_f16_e32 v44, v169
	v_cvt_f32_f16_sdwa v45, v169 dst_sel:DWORD dst_unused:UNUSED_PAD src0_sel:WORD_1
	v_cvt_f32_f16_e32 v46, v170
	v_pk_mul_f32 v[168:169], v[48:49], v[48:49]
	v_cvt_f32_f16_sdwa v47, v170 dst_sel:DWORD dst_unused:UNUSED_PAD src0_sel:WORD_1
	v_cvt_f32_f16_e32 v42, v171
	v_cvt_f32_f16_sdwa v43, v171 dst_sel:DWORD dst_unused:UNUSED_PAD src0_sel:WORD_1
	v_pk_mul_f32 v[170:171], v[44:45], v[44:45]
	v_add_f32_e32 v139, v168, v169
	v_add_f32_e32 v139, v170, v139
	v_add_f32_e32 v139, v171, v139
	v_pk_mul_f32 v[196:197], v[46:47], v[46:47]
	v_pk_mul_f32 v[198:199], v[42:43], v[42:43]
	v_add_f32_e32 v139, v196, v139
	v_add_f32_e32 v139, v197, v139
	v_add_f32_e32 v139, v198, v139
	v_add_f32_e32 v139, v199, v139
	s_waitcnt vmcnt(12)
	v_cvt_f32_f16_e32 v168, v230
	v_cvt_f32_f16_sdwa v169, v230 dst_sel:DWORD dst_unused:UNUSED_PAD src0_sel:WORD_1
	v_cvt_f32_f16_e32 v170, v231
	v_cvt_f32_f16_sdwa v171, v231 dst_sel:DWORD dst_unused:UNUSED_PAD src0_sel:WORD_1
	v_cvt_f32_f16_e32 v172, v232
	v_cvt_f32_f16_sdwa v173, v232 dst_sel:DWORD dst_unused:UNUSED_PAD src0_sel:WORD_1
	v_cvt_f32_f16_e32 v174, v233
	v_cvt_f32_f16_sdwa v175, v233 dst_sel:DWORD dst_unused:UNUSED_PAD src0_sel:WORD_1
	v_pk_fma_f32 v[38:39], v[38:39], v[158:159], v[168:169]
	v_pk_fma_f32 v[40:41], v[40:41], v[156:157], v[170:171]
	v_cvt_pk_f16_f32 v168, v38, v39
	v_cvt_pk_f16_f32 v169, v40, v41
	v_cvt_f32_f16_e32 v40, v168
	v_cvt_f32_f16_sdwa v41, v168 dst_sel:DWORD dst_unused:UNUSED_PAD src0_sel:WORD_1
	v_pk_fma_f32 v[36:37], v[36:37], v[152:153], v[174:175]
	v_pk_fma_f32 v[34:35], v[34:35], v[154:155], v[172:173]
	v_cvt_pk_f16_f32 v171, v36, v37
	v_cvt_f32_f16_e32 v36, v169
	v_cvt_f32_f16_sdwa v37, v169 dst_sel:DWORD dst_unused:UNUSED_PAD src0_sel:WORD_1
	v_cvt_pk_f16_f32 v170, v34, v35
	v_cvt_f32_f16_e32 v38, v170
	v_cvt_f32_f16_sdwa v39, v170 dst_sel:DWORD dst_unused:UNUSED_PAD src0_sel:WORD_1
	v_pk_mul_f32 v[172:173], v[40:41], v[40:41]
	v_cvt_f32_f16_e32 v34, v171
	v_add_f32_e32 v139, v172, v139
	v_cvt_f32_f16_sdwa v35, v171 dst_sel:DWORD dst_unused:UNUSED_PAD src0_sel:WORD_1
	v_pk_mul_f32 v[174:175], v[36:37], v[36:37]
	v_add_f32_e32 v139, v173, v139
	v_add_f32_e32 v139, v174, v139
	v_pk_mul_f32 v[196:197], v[38:39], v[38:39]
	v_add_f32_e32 v139, v175, v139
	v_add_f32_e32 v139, v196, v139
	v_pk_mul_f32 v[208:209], v[34:35], v[34:35]
	v_add_f32_e32 v139, v197, v139
	v_add_f32_e32 v139, v208, v139
	v_add_f32_e32 v139, v209, v139
	s_waitcnt lgkmcnt(0)
	ds_bpermute_b32 v149, v180, v139
	v_lshl_add_u64 v[172:173], s[18:19], 0, v[176:177]
	global_store_dwordx4 v[172:173], v[168:171], off
	s_waitcnt lgkmcnt(0)
	v_add_f32_e32 v139, v139, v149
	ds_bpermute_b32 v149, v181, v139
	s_and_saveexec_b64 s[28:29], s[4:5]
	s_cbranch_execz .LBB0_579
	s_waitcnt lgkmcnt(0)
	v_add_f32_e32 v139, v139, v149
	v_add_u32_e32 v149, s72, v190
	ds_write_b32 v149, v139 offset:2304
; #define LAS __attribute__((address_space(3)))
; __device__ __forceinline__ float shx(float v, int m, int lane) { return __int_as_float(__builtin_amdgcn_ds_bpermute((lane ^ m) << 2, __float_as_int(v))); }
;     __device__ __forceinline__ void operator()(const f32x4 (&acc)[2][2][4][2], const Unit& u, int wr, int wc, int fr, int fq) const {
;         const int lane = fq * 16 + fr, wid = wr * 4 + wc, tid = wid * 64 + lane;
;         const int row0 = u.pm * BM + wr * 64 + fr, col0 = u.pn * BM + wc * 32 + 8 * fq;
;         const int b = (u.pm * BM) >> 12;
;         LAS float* red = (LAS float*)sm; LAS float* rs = red + 1024;
;         f32x4 gv[2][2];
; #pragma unroll
;         for (int bj = 0; bj < 2; ++bj)
; #pragma unroll
;             for (int n = 0; n < 2; ++n) gv[bj][n] = *(const f32x4*)(gate + b * 9216 + col0 + bj * HALF + 4 * n) * coef;
;         h16x8 ov[2][4][2];
; #pragma unroll
;         for (int ai = 0; ai < 2; ++ai)
; #pragma unroll
;             for (int m = 0; m < 4; ++m) {
;                 float sq = 0.f;
; #pragma unroll
;                 for (int bj = 0; bj < 2; ++bj) {
;                     const unsigned off = (unsigned)(row0 + ai * HALF + m * 16) * DM + col0 + bj * HALF;
;                     f32x4 xa, xb;
;                     if (F32IN) { xa = *(const f32x4*)(in32 + off); xb = *(const f32x4*)(in32 + off + 4); }
;                     else { const h16x8 xv = *(const h16x8*)(in16 + off); xa = (f32x4){(float)xv[0], (float)xv[1], (float)xv[2], (float)xv[3]}; xb = (f32x4){(float)xv[4], (float)xv[5], (float)xv[6], (float)xv[7]}; }
;                     h16x8 o;
; #pragma unroll
;                     for (int j = 0; j < 4; ++j) { o[j] = (h16)(xa[j] + gv[bj][0][j] * acc[ai][bj][m][0][j]); o[4 + j] = (h16)(xb[j] + gv[bj][1][j] * acc[ai][bj][m][1][j]); }
;                     if (!FINAL) *(h16x8*)(out + off) = o;
;                     ov[ai][m][bj] = o;
; #pragma unroll
;                     for (int j = 0; j < 8; ++j) sq += (float)o[j] * (float)o[j];
;                 }
;                 sq += shx(sq, 16, lane); sq += shx(sq, 32, lane);
;                 if (fq == 0) red[(ai * HALF + wr * 64 + m * 16 + fr) * 4 + wc] = sq;
;             }
.LBB0_579:
	s_or_b64 exec, exec, s[28:29]
	v_add_u32_e32 v168, 0x28000, v32
	v_mov_b32_e32 v169, v33
	s_nop 0
	v_lshlrev_b64 v[172:173], 1, v[168:169]
	v_readlane_b32 s48, v253, 12
	v_readlane_b32 s49, v253, 13
	v_add_u32_e32 v174, 0x28080, v32
	v_mov_b32_e32 v175, v33
	v_lshl_add_u64 v[168:169], s[48:49], 0, v[172:173]
	v_lshlrev_b64 v[176:177], 1, v[174:175]
	v_lshl_add_u64 v[172:173], s[18:19], 0, v[172:173]
	v_lshl_add_u64 v[174:175], s[48:49], 0, v[176:177]
	s_nop 7
	s_nop 4
	s_waitcnt vmcnt(10)
	v_cvt_f32_f16_e32 v196, v234
	v_cvt_f32_f16_sdwa v197, v234 dst_sel:DWORD dst_unused:UNUSED_PAD src0_sel:WORD_1
	v_cvt_f32_f16_e32 v168, v235
	v_cvt_f32_f16_sdwa v169, v235 dst_sel:DWORD dst_unused:UNUSED_PAD src0_sel:WORD_1
	v_cvt_f32_f16_e32 v198, v236
	v_cvt_f32_f16_sdwa v199, v236 dst_sel:DWORD dst_unused:UNUSED_PAD src0_sel:WORD_1
	v_cvt_f32_f16_e32 v170, v237
	v_cvt_f32_f16_sdwa v171, v237 dst_sel:DWORD dst_unused:UNUSED_PAD src0_sel:WORD_1
	v_pk_fma_f32 v[28:29], v[28:29], v[166:167], v[196:197]
	v_pk_fma_f32 v[30:31], v[30:31], v[164:165], v[168:169]
	v_pk_fma_f32 v[24:25], v[24:25], v[162:163], v[198:199]
	v_pk_fma_f32 v[26:27], v[26:27], v[160:161], v[170:171]
	v_cvt_pk_f16_f32 v168, v28, v29
	v_cvt_pk_f16_f32 v169, v30, v31
	v_cvt_pk_f16_f32 v170, v24, v25
	v_cvt_pk_f16_f32 v171, v26, v27
	global_store_dwordx4 v[172:173], v[168:171], off
	v_cvt_f32_f16_e32 v30, v168
	v_cvt_f32_f16_sdwa v31, v168 dst_sel:DWORD dst_unused:UNUSED_PAD src0_sel:WORD_1
	v_cvt_f32_f16_e32 v26, v169
	v_cvt_f32_f16_sdwa v27, v169 dst_sel:DWORD dst_unused:UNUSED_PAD src0_sel:WORD_1
	v_cvt_f32_f16_e32 v28, v170
	v_pk_mul_f32 v[168:169], v[30:31], v[30:31]
	v_cvt_f32_f16_sdwa v29, v170 dst_sel:DWORD dst_unused:UNUSED_PAD src0_sel:WORD_1
	v_cvt_f32_f16_e32 v24, v171
	v_cvt_f32_f16_sdwa v25, v171 dst_sel:DWORD dst_unused:UNUSED_PAD src0_sel:WORD_1
	v_pk_mul_f32 v[170:171], v[26:27], v[26:27]
	v_add_f32_e32 v139, v168, v169
	v_add_f32_e32 v139, v170, v139
	v_add_f32_e32 v139, v171, v139
	v_pk_mul_f32 v[196:197], v[28:29], v[28:29]
	v_pk_mul_f32 v[198:199], v[24:25], v[24:25]
	v_add_f32_e32 v139, v196, v139
	v_add_f32_e32 v139, v197, v139
	v_add_f32_e32 v139, v198, v139
	v_add_f32_e32 v139, v199, v139
	s_waitcnt vmcnt(10)
	v_cvt_f32_f16_e32 v168, v238
	v_cvt_f32_f16_sdwa v169, v238 dst_sel:DWORD dst_unused:UNUSED_PAD src0_sel:WORD_1
	v_cvt_f32_f16_e32 v170, v239
	v_cvt_f32_f16_sdwa v171, v239 dst_sel:DWORD dst_unused:UNUSED_PAD src0_sel:WORD_1
	v_cvt_f32_f16_e32 v172, v240
	v_cvt_f32_f16_sdwa v173, v240 dst_sel:DWORD dst_unused:UNUSED_PAD src0_sel:WORD_1
	v_cvt_f32_f16_e32 v174, v241
	v_cvt_f32_f16_sdwa v175, v241 dst_sel:DWORD dst_unused:UNUSED_PAD src0_sel:WORD_1
	v_pk_fma_f32 v[20:21], v[20:21], v[158:159], v[168:169]
	v_pk_fma_f32 v[22:23], v[22:23], v[156:157], v[170:171]
	v_cvt_pk_f16_f32 v168, v20, v21
	v_cvt_pk_f16_f32 v169, v22, v23
	v_cvt_f32_f16_e32 v22, v168
	v_cvt_f32_f16_sdwa v23, v168 dst_sel:DWORD dst_unused:UNUSED_PAD src0_sel:WORD_1
	v_pk_fma_f32 v[18:19], v[18:19], v[152:153], v[174:175]
	v_pk_fma_f32 v[16:17], v[16:17], v[154:155], v[172:173]
	v_cvt_pk_f16_f32 v171, v18, v19
	v_cvt_f32_f16_e32 v18, v169
	v_cvt_f32_f16_sdwa v19, v169 dst_sel:DWORD dst_unused:UNUSED_PAD src0_sel:WORD_1
	v_cvt_pk_f16_f32 v170, v16, v17
	v_cvt_f32_f16_e32 v20, v170
	v_cvt_f32_f16_sdwa v21, v170 dst_sel:DWORD dst_unused:UNUSED_PAD src0_sel:WORD_1
	v_pk_mul_f32 v[172:173], v[22:23], v[22:23]
	v_cvt_f32_f16_e32 v16, v171
	v_add_f32_e32 v139, v172, v139
	v_cvt_f32_f16_sdwa v17, v171 dst_sel:DWORD dst_unused:UNUSED_PAD src0_sel:WORD_1
	v_pk_mul_f32 v[174:175], v[18:19], v[18:19]
	v_add_f32_e32 v139, v173, v139
	v_add_f32_e32 v139, v174, v139
	v_pk_mul_f32 v[196:197], v[20:21], v[20:21]
	v_add_f32_e32 v139, v175, v139
	v_add_f32_e32 v139, v196, v139
	v_pk_mul_f32 v[208:209], v[16:17], v[16:17]
	v_add_f32_e32 v139, v197, v139
	v_add_f32_e32 v139, v208, v139
	v_add_f32_e32 v139, v209, v139
	s_waitcnt lgkmcnt(0)
	ds_bpermute_b32 v149, v180, v139
	v_lshl_add_u64 v[172:173], s[18:19], 0, v[176:177]
	global_store_dwordx4 v[172:173], v[168:171], off
	s_waitcnt lgkmcnt(0)
	v_add_f32_e32 v139, v139, v149
	ds_bpermute_b32 v149, v181, v139
	s_and_saveexec_b64 s[28:29], s[4:5]
	s_cbranch_execz .LBB0_581
	s_waitcnt lgkmcnt(0)
	v_add_f32_e32 v139, v139, v149
	v_add_u32_e32 v149, s72, v190
	ds_write_b32 v149, v139 offset:2560
; #define LAS __attribute__((address_space(3)))
; __device__ __forceinline__ float shx(float v, int m, int lane) { return __int_as_float(__builtin_amdgcn_ds_bpermute((lane ^ m) << 2, __float_as_int(v))); }
;     __device__ __forceinline__ void operator()(const f32x4 (&acc)[2][2][4][2], const Unit& u, int wr, int wc, int fr, int fq) const {
;         const int lane = fq * 16 + fr, wid = wr * 4 + wc, tid = wid * 64 + lane;
;         const int row0 = u.pm * BM + wr * 64 + fr, col0 = u.pn * BM + wc * 32 + 8 * fq;
;         const int b = (u.pm * BM) >> 12;
;         LAS float* red = (LAS float*)sm; LAS float* rs = red + 1024;
;         f32x4 gv[2][2];
; #pragma unroll
;         for (int bj = 0; bj < 2; ++bj)
; #pragma unroll
;             for (int n = 0; n < 2; ++n) gv[bj][n] = *(const f32x4*)(gate + b * 9216 + col0 + bj * HALF + 4 * n) * coef;
;         h16x8 ov[2][4][2];
; #pragma unroll
;         for (int ai = 0; ai < 2; ++ai)
; #pragma unroll
;             for (int m = 0; m < 4; ++m) {
;                 float sq = 0.f;
; #pragma unroll
;                 for (int bj = 0; bj < 2; ++bj) {
;                     const unsigned off = (unsigned)(row0 + ai * HALF + m * 16) * DM + col0 + bj * HALF;
;                     f32x4 xa, xb;
;                     if (F32IN) { xa = *(const f32x4*)(in32 + off); xb = *(const f32x4*)(in32 + off + 4); }
;                     else { const h16x8 xv = *(const h16x8*)(in16 + off); xa = (f32x4){(float)xv[0], (float)xv[1], (float)xv[2], (float)xv[3]}; xb = (f32x4){(float)xv[4], (float)xv[5], (float)xv[6], (float)xv[7]}; }
;                     h16x8 o;
; #pragma unroll
;                     for (int j = 0; j < 4; ++j) { o[j] = (h16)(xa[j] + gv[bj][0][j] * acc[ai][bj][m][0][j]); o[4 + j] = (h16)(xb[j] + gv[bj][1][j] * acc[ai][bj][m][1][j]); }
;                     if (!FINAL) *(h16x8*)(out + off) = o;
;                     ov[ai][m][bj] = o;
; #pragma unroll
;                     for (int j = 0; j < 8; ++j) sq += (float)o[j] * (float)o[j];
;                 }
;                 sq += shx(sq, 16, lane); sq += shx(sq, 32, lane);
;                 if (fq == 0) red[(ai * HALF + wr * 64 + m * 16 + fr) * 4 + wc] = sq;
;             }
.LBB0_581:
	s_or_b64 exec, exec, s[28:29]
	v_add_u32_e32 v168, 0x2c000, v32
	v_mov_b32_e32 v169, v33
	s_nop 0
	v_lshlrev_b64 v[172:173], 1, v[168:169]
	v_readlane_b32 s48, v253, 12
	v_readlane_b32 s49, v253, 13
	v_lshl_add_u64 v[176:177], s[18:19], 0, v[172:173]
	v_add_u32_e32 v32, 0x2c080, v32
	v_lshl_add_u64 v[168:169], s[48:49], 0, v[172:173]
	s_nop 5
	v_readlane_b32 s43, v253, 7
	v_readlane_b32 s44, v253, 8
	s_nop 0
	v_readlane_b32 s46, v253, 10
	s_nop 2
	s_waitcnt vmcnt(8)
	v_cvt_f32_f16_e32 v172, v242
	v_cvt_f32_f16_sdwa v173, v242 dst_sel:DWORD dst_unused:UNUSED_PAD src0_sel:WORD_1
	v_cvt_f32_f16_e32 v168, v243
	v_cvt_f32_f16_sdwa v169, v243 dst_sel:DWORD dst_unused:UNUSED_PAD src0_sel:WORD_1
	v_pk_fma_f32 v[12:13], v[12:13], v[166:167], v[172:173]
	s_nop 0
	v_cvt_pk_f16_f32 v172, v12, v13
	v_pk_fma_f32 v[14:15], v[14:15], v[164:165], v[168:169]
	v_cvt_f32_f16_e32 v168, v244
	v_cvt_f32_f16_sdwa v169, v244 dst_sel:DWORD dst_unused:UNUSED_PAD src0_sel:WORD_1
	v_cvt_pk_f16_f32 v173, v14, v15
	v_cvt_f32_f16_e32 v166, v172
	v_cvt_f32_f16_sdwa v167, v172 dst_sel:DWORD dst_unused:UNUSED_PAD src0_sel:WORD_1
	v_pk_fma_f32 v[8:9], v[8:9], v[162:163], v[168:169]
	v_cvt_f32_f16_e32 v164, v173
	v_cvt_pk_f16_f32 v174, v8, v9
	v_cvt_f32_f16_e32 v8, v245
	v_cvt_f32_f16_sdwa v9, v245 dst_sel:DWORD dst_unused:UNUSED_PAD src0_sel:WORD_1
	v_cvt_f32_f16_sdwa v165, v173 dst_sel:DWORD dst_unused:UNUSED_PAD src0_sel:WORD_1
	v_cvt_f32_f16_e32 v162, v174
	v_cvt_f32_f16_sdwa v163, v174 dst_sel:DWORD dst_unused:UNUSED_PAD src0_sel:WORD_1
	v_pk_fma_f32 v[8:9], v[10:11], v[160:161], v[8:9]
	v_lshlrev_b64 v[10:11], 1, v[32:33]
	v_cvt_pk_f16_f32 v175, v8, v9
	global_store_dwordx4 v[176:177], v[172:175], off
	v_lshl_add_u64 v[170:171], s[48:49], 0, v[10:11]
	v_cvt_f32_f16_e32 v160, v175
	v_cvt_f32_f16_sdwa v161, v175 dst_sel:DWORD dst_unused:UNUSED_PAD src0_sel:WORD_1
	v_pk_mul_f32 v[12:13], v[166:167], v[166:167]
	v_lshl_add_u64 v[10:11], s[18:19], 0, v[10:11]
	v_pk_mul_f32 v[14:15], v[164:165], v[164:165]
	v_pk_mul_f32 v[168:169], v[162:163], v[162:163]
	v_pk_mul_f32 v[8:9], v[160:161], v[160:161]
	s_waitcnt vmcnt(8)
	v_cvt_f32_f16_e32 v174, v246
	v_cvt_f32_f16_sdwa v175, v246 dst_sel:DWORD dst_unused:UNUSED_PAD src0_sel:WORD_1
	v_pk_fma_f32 v[4:5], v[4:5], v[158:159], v[174:175]
	v_cvt_f32_f16_e32 v174, v247
	v_cvt_f32_f16_sdwa v175, v247 dst_sel:DWORD dst_unused:UNUSED_PAD src0_sel:WORD_1
	v_cvt_pk_f16_f32 v170, v4, v5
	v_cvt_f32_f16_e32 v158, v170
	v_cvt_f32_f16_sdwa v159, v170 dst_sel:DWORD dst_unused:UNUSED_PAD src0_sel:WORD_1
	v_pk_fma_f32 v[6:7], v[6:7], v[156:157], v[174:175]
	v_cvt_f32_f16_e32 v174, v248
	v_cvt_f32_f16_sdwa v175, v248 dst_sel:DWORD dst_unused:UNUSED_PAD src0_sel:WORD_1
	v_cvt_pk_f16_f32 v171, v6, v7
	v_cvt_f32_f16_e32 v156, v171
	v_cvt_f32_f16_sdwa v157, v171 dst_sel:DWORD dst_unused:UNUSED_PAD src0_sel:WORD_1
	v_pk_fma_f32 v[0:1], v[0:1], v[154:155], v[174:175]
	v_cvt_f32_f16_e32 v174, v249
	v_cvt_f32_f16_sdwa v175, v249 dst_sel:DWORD dst_unused:UNUSED_PAD src0_sel:WORD_1
	v_cvt_pk_f16_f32 v172, v0, v1
	v_pk_mul_f32 v[4:5], v[158:159], v[158:159]
	v_cvt_f32_f16_e32 v154, v172
	v_pk_fma_f32 v[2:3], v[2:3], v[152:153], v[174:175]
	v_cvt_f32_f16_sdwa v155, v172 dst_sel:DWORD dst_unused:UNUSED_PAD src0_sel:WORD_1
	v_cvt_pk_f16_f32 v173, v2, v3
	global_store_dwordx4 v[10:11], v[170:173], off
	v_add_f32_e32 v10, v12, v13
	v_add_f32_e32 v10, v14, v10
	v_add_f32_e32 v10, v15, v10
	v_add_f32_e32 v10, v168, v10
	v_add_f32_e32 v10, v169, v10
	v_add_f32_e32 v8, v8, v10
	v_add_f32_e32 v8, v9, v8
	v_add_f32_e32 v4, v4, v8
	v_pk_mul_f32 v[6:7], v[156:157], v[156:157]
	v_cvt_f32_f16_e32 v152, v173
	v_cvt_f32_f16_sdwa v153, v173 dst_sel:DWORD dst_unused:UNUSED_PAD src0_sel:WORD_1
	v_add_f32_e32 v4, v5, v4
	v_add_f32_e32 v4, v6, v4
	v_pk_mul_f32 v[0:1], v[154:155], v[154:155]
	v_add_f32_e32 v4, v7, v4
	v_add_f32_e32 v0, v0, v4
	v_pk_mul_f32 v[2:3], v[152:153], v[152:153]
	v_add_f32_e32 v0, v1, v0
	v_add_f32_e32 v0, v2, v0
	v_add_f32_e32 v0, v3, v0
	ds_bpermute_b32 v1, v180, v0
	s_waitcnt lgkmcnt(0)
	v_add_f32_e32 v0, v0, v1
	ds_bpermute_b32 v1, v181, v0
	s_and_saveexec_b64 s[28:29], s[4:5]
	s_cbranch_execz .LBB0_583
	s_waitcnt lgkmcnt(0)
	v_add_f32_e32 v0, v0, v1
	v_add_u32_e32 v1, s72, v190
	ds_write_b32 v1, v0 offset:2816
